# diff-attention: per-register part of the ALiBi bias kept in the MFMA C-init registers (refreshed on rescale / diagonal crossing), per-tile part is one f32 add per score; diagonal tile keeps the per-el
# speedup vs baseline: 1.0061x; 1.0039x over previous
; template <int DQK, int DV, bool BIAS> ...
;     ...
;     for (int ks = 0; ks < NKS; ++ks) qf[ks] = ks < 4 ? *(const bf16x8*)(Qw + (size_t)r32 * ldq + ks * 16 + hi * 8) : *(const bf16x8*)(Q2w + (size_t)r32 * ldq2 + (ks - 4) * 16 + hi * 8);
; #pragma unroll
;     for (int ks = 0; ks < 4; ++ks) qf[ks] = scale_frag(qf[ks], cs);
;     if constexpr (DQK == 96) {
;         const float* rp = ropetab + ((size_t)(qpos0 + r32) * 16) * 2;
; #pragma unroll
;         for (int ks = 4; ks < 6; ++ks) {
;             const f32x4 c0 = *(const f32x4*)(rp + ((ks - 4) * 8 + hi * 4) * 2), c1 = *(const f32x4*)(rp + ((ks - 4) * 8 + hi * 4 + 2) * 2);
;             const u32x4 w = __builtin_bit_cast(u32x4, qf[ks]); u32x4 ow;
;             { const float a = bflo(w.x) * cs, b = bfhi(w.x) * cs; ow.x = cvtpk(a * c0[0] - b * c0[1], a * c0[1] + b * c0[0]); }
;             { const float a = bflo(w.y) * cs, b = bfhi(w.y) * cs; ow.y = cvtpk(a * c0[2] - b * c0[3], a * c0[3] + b * c0[2]); }
;             { const float a = bflo(w.z) * cs, b = bfhi(w.z) * cs; ow.z = cvtpk(a * c1[0] - b * c1[1], a * c1[1] + b * c1[0]); }
;             { const float a = bflo(w.w) * cs, b = bfhi(w.w) * cs; ow.w = cvtpk(a * c1[2] - b * c1[3], a * c1[3] + b * c1[2]); }
;             qf[ks] = __builtin_bit_cast(bf16x8, ow);
;         }
;     }
; #pragma unroll
;     for (int d = 0; d < NDT; ++d)
; #pragma unroll
;         for (int r = 0; r < 16; ++r) o[d][r] = 0.f;
; #pragma unroll
;     for (int ks = 0; ks < NKS; ++ks) asm volatile("" : "+v"(qf[ks]));
;     float mhat = 0.f, l = 0.f; f32x16 negm;
; __device__ __forceinline__ void attn_phase(PPtr P, int li, LAS unsigned char* lds, int vcu, int wave, int lane) {
;     bf16_t* proj = (bf16_t*)(P->ws + OFF_PROJ); bf16_t* mlaq = (bf16_t*)(P->ws + OFF_MLAQ); const bf16_t* mlakv = (const bf16_t*)(P->ws + OFF_MLAKV);
;     const int r32 = lane & 31, hi = lane >> 5;
;     {
;         const int b = vcu >> 6, h = (vcu >> 4) & 3, qb = vcu & 15;
;         const size_t seq0 = (size_t)b * SEQL, qrow = seq0 + qb * 256 + wave * 32;
;         const float slope = __builtin_amdgcn_exp2f(-2.f * (float)(h + 1));
;         f32x16 o1[4], o2[4];
;         attn_pass<64, 128, true>(lds, proj + qrow * LDP + C_AQ + h * 128, LDP, nullptr, 0, proj + seq0 * LDP + C_AK + h * 128, LDP, nullptr, 0, proj + seq0 * LDP + C_AV + h * 128, LDP, qb * 256 + wave * 32, 0.125f * LOG2E, slope * LOG2E, nullptr, o1);
.LBB0_573:
	s_cmp_lt_i32 s24, 5
	s_cselect_b64 s[4:5], -1, 0
	s_cmp_gt_i32 s25, 4
	s_cselect_b64 s[6:7], -1, 0
	s_and_b64 s[4:5], s[4:5], s[6:7]
	s_andn2_b64 vcc, exec, s[4:5]
	s_cbranch_vccnz .LBB0_751
	s_mov_b64 s[20:21], s[0:1]
	v_mov_b32_e32 v169, v1
	s_load_dwordx2 s[16:17], s[20:21], 0x118
	s_ashr_i32 s4, s33, 6
	v_readfirstlane_b32 s3, v169
	s_ashr_i32 s50, s3, 6
	s_ashr_i32 s5, s4, 31
	s_lshl_b32 s3, s33, 8
	s_lshl_b64 s[6:7], s[4:5], 12
	s_and_b32 s27, s3, 0xf00
	s_lshl_b32 s46, s50, 5
	s_bfe_u32 s8, s33, 0x20004
	s_or_b32 s3, s6, s27
	s_ashr_i32 s47, s46, 31
	s_add_u32 s5, s3, s46
	s_addc_u32 s6, s7, s47
	s_not_b32 s3, s8
	s_mulk_i32 s6, 0x1940
	s_mul_hi_u32 s7, s5, 0x1940
	s_lshl_b32 s3, s3, 1
	s_add_i32 s7, s7, s6
	s_mulk_i32 s5, 0x1940
	s_waitcnt lgkmcnt(0)
	s_add_u32 s5, s16, s5
	v_mov_b32_e32 v32, v1
	s_addc_u32 s6, s17, s7
	s_lshl_b32 s9, s8, 8
	s_add_u32 s18, s5, s9
	v_and_b32_e32 v33, 31, v32
	v_mul_u32_u24_e32 v2, 0xca0, v33
	s_addc_u32 s19, s6, 0
	v_bfe_u32 v34, v32, 5, 1
	v_lshlrev_b32_e32 v150, 1, v2
	v_mov_b32_e32 v151, 0
	v_lshl_add_u64 v[2:3], s[18:19], 0, v[150:151]
	v_lshlrev_b32_e32 v150, 4, v34
	v_lshl_add_u64 v[18:19], v[2:3], 0, v[150:151]
	global_load_dwordx4 v[2:5], v[18:19], off
	global_load_dwordx4 v[6:9], v[18:19], off offset:32
	global_load_dwordx4 v[10:13], v[18:19], off offset:64
	global_load_dwordx4 v[14:17], v[18:19], off offset:96
	s_movk_i32 s7, 0x1940
	s_mov_b32 s6, 0x3e38aa3b
	s_mul_i32 s49, s4, 0x1940000
	s_mul_hi_i32 s48, s4, 0x1940000
	s_add_u32 s4, s16, s49
	s_addc_u32 s5, s17, s48
	s_add_u32 s4, s4, s9
	s_addc_u32 s5, s5, 0
	s_mov_b32 s8, 0x65000
	v_lshlrev_b32_e32 v173, 2, v34
	s_mov_b32 s22, 0xc1000000
	s_mov_b32 s34, 0xc1200000
	s_mov_b32 s36, 0xc1800000
	s_mov_b32 s38, 0xc1900000
	s_mov_b32 s40, 0xc1c00000
	s_mov_b32 s42, 0xc1d00000
	s_mov_b32 s51, 0
	s_mov_b32 s23, 0xc1100000
	s_mov_b32 s35, 0xc1300000
	s_mov_b32 s37, 0xc1880000
	s_mov_b32 s39, 0xc1980000
	s_mov_b32 s41, 0xc1c80000
	s_mov_b32 s43, 0xc1d80000
	s_mov_b32 s52, 0x41000000
	v_mov_b32_e32 v176, v151
	v_mov_b32_e32 v66, v151
	v_mov_b32_e32 v67, v151
	v_mov_b32_e32 v68, v151
	v_mov_b32_e32 v69, v151
	v_mov_b32_e32 v70, v151
	v_mov_b32_e32 v71, v151
	v_mov_b32_e32 v72, v151
	v_mov_b32_e32 v73, v151
	v_mov_b32_e32 v74, v151
	v_mov_b32_e32 v75, v151
	v_mov_b32_e32 v76, v151
	v_mov_b32_e32 v77, v151
	v_mov_b32_e32 v78, v151
	v_mov_b32_e32 v79, v151
	v_mov_b32_e32 v80, v151
	v_mov_b32_e32 v81, v151
	s_waitcnt vmcnt(0)
; __device__ __forceinline__ unsigned cvtpk(float lo, float hi) { typedef __bf16 bf2 __attribute__((ext_vector_type(2))); f32x2 v = {lo, hi}; bf2 b = __builtin_convertvector(v, bf2); return __builtin_bit_cast(unsigned, b); }
; template <int DQK, int DV, bool BIAS> ...
;     ...
;     for (int ks = 0; ks < NKS; ++ks) qf[ks] = ks < 4 ? *(const bf16x8*)(Qw + (size_t)r32 * ldq + ks * 16 + hi * 8) : *(const bf16x8*)(Q2w + (size_t)r32 * ldq2 + (ks - 4) * 16 + hi * 8);
; #pragma unroll
;     for (int ks = 0; ks < 4; ++ks) qf[ks] = scale_frag(qf[ks], cs);
;     if constexpr (DQK == 96) {
;         const float* rp = ropetab + ((size_t)(qpos0 + r32) * 16) * 2;
; #pragma unroll
;         for (int ks = 4; ks < 6; ++ks) {
;             const f32x4 c0 = *(const f32x4*)(rp + ((ks - 4) * 8 + hi * 4) * 2), c1 = *(const f32x4*)(rp + ((ks - 4) * 8 + hi * 4 + 2) * 2);
;             const u32x4 w = __builtin_bit_cast(u32x4, qf[ks]); u32x4 ow;
;             { const float a = bflo(w.x) * cs, b = bfhi(w.x) * cs; ow.x = cvtpk(a * c0[0] - b * c0[1], a * c0[1] + b * c0[0]); }
;             { const float a = bflo(w.y) * cs, b = bfhi(w.y) * cs; ow.y = cvtpk(a * c0[2] - b * c0[3], a * c0[3] + b * c0[2]); }
;             { const float a = bflo(w.z) * cs, b = bfhi(w.z) * cs; ow.z = cvtpk(a * c1[0] - b * c1[1], a * c1[1] + b * c1[0]); }
;             { const float a = bflo(w.w) * cs, b = bfhi(w.w) * cs; ow.w = cvtpk(a * c1[2] - b * c1[3], a * c1[3] + b * c1[2]); }
;             qf[ks] = __builtin_bit_cast(bf16x8, ow);
;         }
;     }
; #pragma unroll
;     for (int d = 0; d < NDT; ++d)
; #pragma unroll
;         for (int r = 0; r < 16; ++r) o[d][r] = 0.f;
; #pragma unroll
;     for (int ks = 0; ks < NKS; ++ks) asm volatile("" : "+v"(qf[ks]));
;     float mhat = 0.f, l = 0.f; f32x16 negm;
; #pragma unroll
;     for (int r = 0; r < 16; ++r) negm[r] = 0.f;
;     constexpr int TPB = (DV == 64) ? 2 : 1, NG = SEQL / 64 / TPB;
;     u32x4 kreg[TPB], k2reg[TPB], vreg[TPB][NVL];
;     const bf16_t* kptr = Kg + (size_t)(tid >> 3) * ldk + (tid & 7) * 8;
;     const bf16_t* k2ptr = (DQK == 96) ? K2g + (size_t)(tid >> 2) * ldk2 + (tid & 3) * 8 : nullptr;
;     ...
;     u32x4 pw[4];
; #pragma unroll
;     for (int j = 0; j < TPB; ++j) { ATT_LOAD(j, j); ATT_STORE(j, j); }
; #pragma unroll
;     for (int j = 0; j < TPB; ++j) ATT_LOAD(TPB + j, j);
;     const float qp = (float)(qpos0 + r32);
	v_lshlrev_b32_e32 v18, 16, v2
	v_and_b32_e32 v19, 0xffff0000, v2
	v_lshlrev_b32_e32 v2, 16, v3
	v_and_b32_e32 v3, 0xffff0000, v3
	v_lshlrev_b32_e32 v30, 16, v14
	v_pk_mul_f32 v[2:3], v[2:3], s[6:7] op_sel_hi:[1,0]
	v_and_b32_e32 v31, 0xffff0000, v14
	v_cvt_pk_bf16_f32 v115, v2, v3
	v_pk_mul_f32 v[2:3], v[30:31], s[6:7] op_sel_hi:[1,0]
	v_lshlrev_b32_e32 v22, 16, v6
	v_cvt_pk_bf16_f32 v126, v2, v3
	v_lshlrev_b32_e32 v2, 16, v15
	v_and_b32_e32 v3, 0xffff0000, v15
	v_pk_mul_f32 v[2:3], v[2:3], s[6:7] op_sel_hi:[1,0]
	v_and_b32_e32 v23, 0xffff0000, v6
	v_cvt_pk_bf16_f32 v127, v2, v3
	v_lshlrev_b32_e32 v2, 16, v16
	v_and_b32_e32 v3, 0xffff0000, v16
	v_pk_mul_f32 v[2:3], v[2:3], s[6:7] op_sel_hi:[1,0]
	v_lshlrev_b32_e32 v24, 16, v8
	v_cvt_pk_bf16_f32 v128, v2, v3
	v_lshlrev_b32_e32 v2, 16, v17
	v_and_b32_e32 v3, 0xffff0000, v17
	v_and_b32_e32 v25, 0xffff0000, v8
	v_pk_mul_f32 v[22:23], v[22:23], s[6:7] op_sel_hi:[1,0]
	v_pk_mul_f32 v[2:3], v[2:3], s[6:7] op_sel_hi:[1,0]
	v_lshlrev_b32_e32 v20, 16, v4
	v_and_b32_e32 v21, 0xffff0000, v4
	v_lshlrev_b32_e32 v4, 16, v5
	v_and_b32_e32 v5, 0xffff0000, v5
	v_pk_mul_f32 v[24:25], v[24:25], s[6:7] op_sel_hi:[1,0]
	v_cvt_pk_bf16_f32 v118, v22, v23
	v_cvt_pk_bf16_f32 v129, v2, v3
	v_ashrrev_i32_e32 v22, 3, v32
	v_mov_b64_e32 v[2:3], s[4:5]
	v_lshlrev_b32_e32 v23, 4, v32
	v_pk_mul_f32 v[4:5], v[4:5], s[6:7] op_sel_hi:[1,0]
	v_cvt_pk_bf16_f32 v120, v24, v25
	v_mad_i64_i32 v[2:3], s[10:11], v22, s7, v[2:3]
	v_and_b32_e32 v14, 0x70, v23
	v_mov_b32_e32 v15, v151
	v_bfe_u32 v24, v32, 2, 6
	v_cvt_pk_bf16_f32 v117, v4, v5
	v_lshl_add_u64 v[144:145], v[2:3], 0, v[14:15]
	v_subrev_u32_e32 v232, s4, v144
	s_sub_u32 s98, s4, s16
	s_subb_u32 s99, s5, s17
	v_mul_u32_u24_e32 v2, 0xca0, v24
	v_lshlrev_b32_e32 v4, 3, v32
	v_lshlrev_b32_e32 v2, 1, v2
	v_mov_b32_e32 v3, v151
	v_and_b32_e32 v25, 24, v4
	v_lshl_add_u64 v[2:3], s[4:5], 0, v[2:3]
	v_lshlrev_b32_e32 v4, 1, v25
	v_mov_b32_e32 v5, v151
	v_lshl_add_u64 v[16:17], v[2:3], 0, v[4:5]
	v_and_b32_e32 v2, 0xffffffe0, v22
	v_lshlrev_b32_e32 v6, 16, v7
	v_and_b32_e32 v7, 0xffff0000, v7
	v_lshlrev_b32_e32 v8, 16, v9
	v_and_b32_e32 v9, 0xffff0000, v9
	v_lshlrev_b32_e32 v26, 16, v10
	v_and_b32_e32 v27, 0xffff0000, v10
	v_lshlrev_b32_e32 v10, 16, v11
	v_and_b32_e32 v11, 0xffff0000, v11
	v_lshlrev_b32_e32 v28, 16, v12
	v_and_b32_e32 v29, 0xffff0000, v12
	v_lshlrev_b32_e32 v12, 16, v13
	v_and_b32_e32 v13, 0xffff0000, v13
	v_pk_mul_f32 v[18:19], v[18:19], s[6:7] op_sel_hi:[1,0]
	v_ashrrev_i32_e32 v3, 31, v2
	v_pk_mul_f32 v[20:21], v[20:21], s[6:7] op_sel_hi:[1,0]
	v_pk_mul_f32 v[6:7], v[6:7], s[6:7] op_sel_hi:[1,0]
	v_pk_mul_f32 v[8:9], v[8:9], s[6:7] op_sel_hi:[1,0]
	v_pk_mul_f32 v[26:27], v[26:27], s[6:7] op_sel_hi:[1,0]
	v_pk_mul_f32 v[10:11], v[10:11], s[6:7] op_sel_hi:[1,0]
	v_pk_mul_f32 v[28:29], v[28:29], s[6:7] op_sel_hi:[1,0]
	v_pk_mul_f32 v[12:13], v[12:13], s[6:7] op_sel_hi:[1,0]
	v_cvt_pk_bf16_f32 v114, v18, v19
	v_lshlrev_b64 v[18:19], 1, v[2:3]
	v_cvt_pk_bf16_f32 v116, v20, v21
	v_cvt_pk_bf16_f32 v119, v6, v7
	v_cvt_pk_bf16_f32 v121, v8, v9
	v_cvt_pk_bf16_f32 v122, v26, v27
	v_cvt_pk_bf16_f32 v123, v10, v11
	v_cvt_pk_bf16_f32 v124, v28, v29
	v_cvt_pk_bf16_f32 v125, v12, v13
	v_lshl_add_u64 v[10:11], v[16:17], 0, v[18:19]
	global_load_dwordx4 v[2:5], v[144:145], off offset:1024
	global_load_dwordx4 v[6:9], v[10:11], off offset:2048
	v_add_u32_e32 v10, 0x200, v32
	v_ashrrev_i32_e32 v10, 3, v10
	v_and_b32_e32 v10, 0xffffffe0, v10
	v_ashrrev_i32_e32 v11, 31, v10
	v_lshlrev_b64 v[20:21], 1, v[10:11]
	v_lshl_add_u64 v[10:11], v[16:17], 0, v[20:21]
	global_load_dwordx4 v[10:13], v[10:11], off offset:2048
	s_movk_i32 s6, 0x90
	v_mul_lo_u32 v15, v22, s6
	s_mov_b64 s[10:11], 0x65800
	v_and_b32_e32 v22, 0xfc0, v23
	v_and_b32_e32 v27, 48, v23
	v_add_u32_e32 v15, 0, v15
	v_and_b32_e32 v23, 0xfffff000, v23
	v_add3_u32 v22, 0, v22, v27
	v_add_u32_e32 v168, v15, v14
	v_lshl_add_u64 v[14:15], v[16:17], 0, s[10:11]
	v_add_u32_e32 v171, v22, v23
	v_lshl_add_u64 v[16:17], v[14:15], 0, v[18:19]
	v_add_co_u32_e32 v22, vcc, s8, v144
	v_lshl_add_u64 v[14:15], v[14:15], 0, v[20:21]
	s_nop 0
	v_addc_co_u32_e32 v23, vcc, 0, v145, vcc
	global_load_dwordx4 v[130:133], v[16:17], off
	global_load_dwordx4 v[134:137], v[14:15], off
	global_load_dwordx4 v[138:141], v[22:23], off offset:1024
	v_cvt_f32_i32_e32 v28, s3
	s_add_i32 s3, s46, s27
	v_lshrrev_b32_e32 v26, 2, v32
	s_waitcnt vmcnt(5)
	ds_write_b128 v168, v[2:5]
	s_waitcnt vmcnt(4)
	ds_write_b128 v171, v[6:9] offset:18432
	s_waitcnt vmcnt(3)
	ds_write_b128 v171, v[10:13] offset:26624
	v_or_b32_e32 v2, s3, v33
	v_cvt_f32_i32_e32 v172, v2
	v_and_or_b32 v2, v26, 3, v173
	v_lshlrev_b32_e32 v3, 1, v32
	v_mad_u32_u24 v22, v33, s6, 0
	v_lshl_add_u32 v2, v2, 6, 0
	v_and_b32_e32 v3, 32, v3
	s_or_b32 s6, s49, s9
	v_exp_f32_e32 v27, v28
	v_add3_u32 v174, v2, v3, v25
	v_mov_b32_e32 v2, s6
	v_mov_b32_e32 v3, s48
	v_mad_u64_u32 v[2:3], s[6:7], v24, s7, v[2:3]
	v_and_b32_e32 v4, 3, v32
	v_lshl_or_b32 v2, v4, 4, v2
	v_lshl_add_u64 v[4:5], v[2:3], 0, v[20:21]
	v_lshl_add_u64 v[2:3], v[2:3], 0, v[18:19]
	v_mov_b32_e32 v16, v151
	v_mov_b32_e32 v17, v151
	v_mbcnt_lo_u32_b32 v18, -1, 0
	v_mul_f32_e32 v142, 0x3fb8aa3b, v27
	v_mov_b32_e32 v231, v4
	v_lshl_add_u64 v[146:147], s[16:17], 0, v[4:5]
	v_mov_b32_e32 v230, v2
	v_lshl_add_u64 v[148:149], s[16:17], 0, v[2:3]
	v_mov_b32_e32 v2, v151
	v_mov_b32_e32 v3, v151
	v_mov_b32_e32 v4, v151
	v_mov_b32_e32 v5, v151
	v_mov_b32_e32 v6, v151
	v_mov_b32_e32 v7, v151
	v_mov_b32_e32 v8, v151
	v_mov_b32_e32 v9, v151
	v_mov_b32_e32 v10, v151
	v_mov_b32_e32 v11, v151
	v_mov_b32_e32 v12, v151
	v_mov_b32_e32 v13, v151
	v_mov_b32_e32 v14, v151
	v_mov_b32_e32 v15, v151
	s_mov_b32 s10, -2.0
	v_add_u32_e32 v175, v22, v150
	v_mbcnt_hi_u32_b32 v170, -1, v18
	v_mov_b64_e32 v[32:33], v[16:17]
	v_mov_b64_e32 v[48:49], v[16:17]
	v_mov_b64_e32 v[64:65], v[16:17]
	v_mov_b32_e32 v143, v142
	s_mov_b64 s[6:7], 0
	s_mov_b32 s8, 0xc2000000
	s_mov_b32 s11, 0xc0400000
	v_mov_b64_e32 v[30:31], v[14:15]
	v_mov_b64_e32 v[28:29], v[12:13]
	v_mov_b64_e32 v[26:27], v[10:11]
	v_mov_b64_e32 v[24:25], v[8:9]
	v_mov_b64_e32 v[22:23], v[6:7]
	v_mov_b64_e32 v[20:21], v[4:5]
	v_mov_b64_e32 v[18:19], v[2:3]
	v_mov_b64_e32 v[46:47], v[14:15]
	v_mov_b64_e32 v[44:45], v[12:13]
	v_mov_b64_e32 v[42:43], v[10:11]
	v_mov_b64_e32 v[40:41], v[8:9]
	v_mov_b64_e32 v[38:39], v[6:7]
	v_mov_b64_e32 v[36:37], v[4:5]
	v_mov_b64_e32 v[34:35], v[2:3]
	v_mov_b64_e32 v[62:63], v[14:15]
	v_mov_b64_e32 v[60:61], v[12:13]
	v_mov_b64_e32 v[58:59], v[10:11]
	v_mov_b64_e32 v[56:57], v[8:9]
	v_mov_b64_e32 v[54:55], v[6:7]
	v_mov_b64_e32 v[52:53], v[4:5]
	v_mov_b64_e32 v[50:51], v[2:3]
	v_mov_b32_e32 v250, 0
	v_cvt_u32_f32_e32 v252, v172
	s_nop 0
	v_readfirstlane_b32 s96, v252
	s_nop 3
	s_lshr_b32 s96, s96, 6
	s_mov_b32 s97, 3
	s_branch .LBB0_576

; #define LAS __attribute__((address_space(3)))
; template <int DQK, int DV, bool BIAS> ...
;     ...
;     for (int g = 0; g < NG; ++g) {
;         const int pair = g & 1;
;         __syncthreads();
;         if (g + 1 < NG) {
; #pragma unroll
;             for (int j = 0; j < TPB; ++j) ATT_STORE((pair ^ 1) * TPB + j, j);
;             if (g + 2 < NG) {
; #pragma unroll
;                 for (int j = 0; j < TPB; ++j) ATT_LOAD((g + 2) * TPB + j, j);
;             }
;         }
; #pragma unroll
;       for (int sub = 0; sub < TPB; ++sub) {
;         const int t = g * TPB + sub, buf = pair * TPB + sub, vcur = buf;
;         f32x16 p0, p1;
;         const LAS unsigned char* kb = lds + buf * KBUF + r32 * KP + hi * 16;
; #pragma unroll
;         for (int ks = 0; ks < NKS; ++ks) {
;             const bf16x8 k0 = *(const LAS bf16x8*)(kb + ks * 32), k1 = *(const LAS bf16x8*)(kb + 32 * KP + ks * 32);
;             if (ks == 0) { p0 = __builtin_amdgcn_mfma_f32_32x32x16_bf16(k0, qf[0], negm, 0, 0, 0); p1 = __builtin_amdgcn_mfma_f32_32x32x16_bf16(k1, qf[0], negm, 0, 0, 0); }
;             else { p0 = __builtin_amdgcn_mfma_f32_32x32x16_bf16(k0, qf[ks], p0, 0, 0, 0); p1 = __builtin_amdgcn_mfma_f32_32x32x16_bf16(k1, qf[ks], p1, 0, 0, 0); }
;         }
;         if (BIAS) {
;             asm volatile("s_nop 15\n\ts_nop 7" : "+v"(p0), "+v"(p1));
;             const float d0 = qp - (float)(t * 64 + 4 * hi);
; #pragma unroll
;             for (int r = 0; r < 16; ++r) { const float dk = d0 - (float)((r & 3) + 8 * (r >> 2)); p0[r] = p0[r] - sl2 * fabsf(dk); p1[r] = p1[r] - sl2 * fabsf(dk - 32.f); }
;         } else {
;             asm volatile("s_nop 15\n\ts_nop 7" : "+v"(p0), "+v"(p1));
.LBB0_578:
	s_mov_b32 s100, s51
	s_cmp_lt_u32 s100, s96
	s_cselect_b32 s101, 1, 2
	s_cmp_eq_u32 s100, s96
	s_cselect_b32 s101, 0, s101
	s_cmp_eq_u32 s101, s97
	s_cbranch_scc1 .Lcb1_ok
	s_mov_b32 s97, s101
	s_cmp_eq_u32 s101, 1
	s_cselect_b32 s100, 0x3f800000, 0xbf800000
	s_cmp_eq_u32 s101, 0
	s_cselect_b32 s100, 0, s100
	v_mul_f32_e32 v251, s100, v142
	v_fmamk_f32 v66, v251, 0x00000000, v250
	v_fmamk_f32 v67, v251, 0x3f800000, v250
	v_fmamk_f32 v68, v251, 0x40000000, v250
	v_fmamk_f32 v69, v251, 0x40400000, v250
	v_fmamk_f32 v70, v251, 0x41000000, v250
	v_fmamk_f32 v71, v251, 0x41100000, v250
	v_fmamk_f32 v72, v251, 0x41200000, v250
	v_fmamk_f32 v73, v251, 0x41300000, v250
	v_fmamk_f32 v74, v251, 0x41800000, v250
	v_fmamk_f32 v75, v251, 0x41880000, v250
	v_fmamk_f32 v76, v251, 0x41900000, v250
	v_fmamk_f32 v77, v251, 0x41980000, v250
	v_fmamk_f32 v78, v251, 0x41c00000, v250
	v_fmamk_f32 v79, v251, 0x41c80000, v250
	v_fmamk_f32 v80, v251, 0x41d00000, v250
	v_fmamk_f32 v81, v251, 0x41d80000, v250
	v_fmamk_f32 v234, v251, 0x42000000, v250
	v_fmamk_f32 v235, v251, 0x42040000, v250
	v_fmamk_f32 v236, v251, 0x42080000, v250
	v_fmamk_f32 v237, v251, 0x420c0000, v250
	v_fmamk_f32 v238, v251, 0x42200000, v250
	v_fmamk_f32 v239, v251, 0x42240000, v250
	v_fmamk_f32 v240, v251, 0x42280000, v250
	v_fmamk_f32 v241, v251, 0x422c0000, v250
	v_fmamk_f32 v242, v251, 0x42400000, v250
	v_fmamk_f32 v243, v251, 0x42440000, v250
	v_fmamk_f32 v244, v251, 0x42480000, v250
	v_fmamk_f32 v245, v251, 0x424c0000, v250
	v_fmamk_f32 v246, v251, 0x42600000, v250
	v_fmamk_f32 v247, v251, 0x42640000, v250
	v_fmamk_f32 v248, v251, 0x42680000, v250
	v_fmamk_f32 v249, v251, 0x426c0000, v250
	s_nop 1
.Lcb1_ok:
	ds_read_b128 v[82:85], v175
	ds_read_b128 v[152:155], v175 offset:32
	ds_read_b128 v[156:159], v175 offset:4608
	ds_read_b128 v[160:163], v175 offset:4640
	v_cvt_f32_u32_e32 v150, v173
	s_waitcnt lgkmcnt(3)
	v_mfma_f32_32x32x16_bf16 v[98:113], v[82:85], v[114:117], v[66:81]
	v_sub_f32_e32 v178, v172, v150
	v_add_f32_e32 v179, -1.0, v178
	s_waitcnt lgkmcnt(1)
	v_mfma_f32_32x32x16_bf16 v[82:97], v[156:159], v[114:117], v[234:249]
	v_mfma_f32_32x32x16_bf16 v[98:113], v[152:155], v[118:121], v[98:113]
	ds_read_b128 v[152:155], v175 offset:64
	ds_read_b128 v[156:159], v175 offset:96
	s_waitcnt lgkmcnt(2)
	v_mfma_f32_32x32x16_bf16 v[82:97], v[160:163], v[118:121], v[82:97]
	s_waitcnt lgkmcnt(1)
	v_mfma_f32_32x32x16_bf16 v[98:113], v[152:155], v[122:125], v[98:113]
	ds_read_b128 v[152:155], v175 offset:4672
	ds_read_b128 v[160:163], v175 offset:4704
	s_waitcnt lgkmcnt(1)
	v_mfma_f32_32x32x16_bf16 v[82:97], v[152:155], v[122:125], v[82:97]
	v_mfma_f32_32x32x16_bf16 v[98:113], v[156:159], v[126:129], v[98:113]
	s_waitcnt lgkmcnt(0)
	v_mfma_f32_32x32x16_bf16 v[82:97], v[160:163], v[126:129], v[82:97]
	s_nop 15
	s_nop 7
	s_nop 9
	s_cmp_eq_u32 s51, s96
	s_cbranch_scc1 .Lcb1_d
	v_mul_f32_e64 v252, -v251, v178
	v_add_f32_e32 v156, v252, v98
	v_add_f32_e32 v157, v252, v99
	v_add_f32_e32 v99, v252, v83
	v_add_f32_e32 v98, v252, v82
	v_add_f32_e32 v161, v252, v101
	v_add_f32_e32 v160, v252, v100
	v_add_f32_e32 v153, v252, v85
	v_add_f32_e32 v152, v252, v84
	v_add_f32_e32 v165, v252, v103
	v_add_f32_e32 v164, v252, v102
	v_add_f32_e32 v103, v252, v87
	v_add_f32_e32 v102, v252, v86
	v_add_f32_e32 v167, v252, v105
	v_add_f32_e32 v166, v252, v104
	v_add_f32_e32 v155, v252, v89
	v_add_f32_e32 v154, v252, v88
	v_add_f32_e32 v159, v252, v107
	v_add_f32_e32 v158, v252, v106
	v_add_f32_e32 v101, v252, v91
	v_add_f32_e32 v100, v252, v90
	v_add_f32_e32 v163, v252, v109
	v_add_f32_e32 v162, v252, v108
	v_add_f32_e32 v105, v252, v93
	v_add_f32_e32 v104, v252, v92
	v_add_f32_e32 v111, v252, v111
	v_add_f32_e32 v110, v252, v110
	v_add_f32_e32 v107, v252, v95
	v_add_f32_e32 v106, v252, v94
	v_add_f32_e32 v113, v252, v113
	v_add_f32_e32 v112, v252, v112
	v_add_f32_e32 v109, v252, v97
	v_add_f32_e32 v108, v252, v96
	s_branch .Lcb1_j
.Lcb1_d:
	v_fma_f32 v156, -v142, |v178|, v98
	v_fma_f32 v157, -v143, |v179|, v99
	v_pk_add_f32 v[98:99], v[178:179], s[8:9] op_sel_hi:[1,0]
	s_nop 0
	v_fma_f32 v99, -v143, |v99|, v83
	v_fma_f32 v98, -v142, |v98|, v82
	v_pk_add_f32 v[82:83], v[178:179], s[10:11] op_sel_hi:[0,1]
	v_fma_f32 v161, -v143, |v83|, v101
	v_fma_f32 v160, -v142, |v82|, v100
	v_pk_add_f32 v[82:83], v[82:83], s[8:9] op_sel_hi:[1,0]
	v_fma_f32 v153, -v143, |v83|, v85
	v_fma_f32 v152, -v142, |v82|, v84
	v_pk_add_f32 v[82:83], v[178:179], s[22:23] op_sel_hi:[0,1]
	v_fma_f32 v165, -v143, |v83|, v103
	v_fma_f32 v164, -v142, |v82|, v102
	v_pk_add_f32 v[82:83], v[82:83], s[8:9] op_sel_hi:[1,0]
	v_fma_f32 v103, -v143, |v83|, v87
	v_fma_f32 v102, -v142, |v82|, v86
	v_pk_add_f32 v[82:83], v[178:179], s[34:35] op_sel_hi:[0,1]
	v_fma_f32 v167, -v143, |v83|, v105
	v_fma_f32 v166, -v142, |v82|, v104
	v_pk_add_f32 v[82:83], v[82:83], s[8:9] op_sel_hi:[1,0]
	v_fma_f32 v155, -v143, |v83|, v89
	v_fma_f32 v154, -v142, |v82|, v88
	v_pk_add_f32 v[82:83], v[178:179], s[36:37] op_sel_hi:[0,1]
	v_fma_f32 v159, -v143, |v83|, v107
	v_fma_f32 v158, -v142, |v82|, v106
	v_pk_add_f32 v[82:83], v[82:83], s[8:9] op_sel_hi:[1,0]
	v_fma_f32 v101, -v143, |v83|, v91
	v_fma_f32 v100, -v142, |v82|, v90
	v_pk_add_f32 v[82:83], v[178:179], s[38:39] op_sel_hi:[0,1]
	v_fma_f32 v163, -v143, |v83|, v109
	v_fma_f32 v162, -v142, |v82|, v108
	v_pk_add_f32 v[82:83], v[82:83], s[8:9] op_sel_hi:[1,0]
	v_fma_f32 v105, -v143, |v83|, v93
	v_fma_f32 v104, -v142, |v82|, v92
	v_pk_add_f32 v[82:83], v[178:179], s[40:41] op_sel_hi:[0,1]
	v_fma_f32 v111, -v143, |v83|, v111
	v_fma_f32 v110, -v142, |v82|, v110
	v_pk_add_f32 v[82:83], v[82:83], s[8:9] op_sel_hi:[1,0]
	v_fma_f32 v107, -v143, |v83|, v95
	v_fma_f32 v106, -v142, |v82|, v94
	v_pk_add_f32 v[82:83], v[178:179], s[42:43] op_sel_hi:[0,1]
	v_fma_f32 v113, -v143, |v83|, v113
	v_fma_f32 v112, -v142, |v82|, v112
	v_pk_add_f32 v[82:83], v[82:83], s[8:9] op_sel_hi:[1,0]
	v_fma_f32 v109, -v143, |v83|, v97
	v_fma_f32 v108, -v142, |v82|, v96
; __device__ __forceinline__ float max3f(float a, float b, float c) { float r; asm("v_max3_f32 %0, %1, %2, %3" : "=v"(r) : "v"(a), "v"(b), "v"(c)); return r; }
; template <int DQK, int DV, bool BIAS> ...
;     ...
;         float mxa = max3f(p0[0], p0[1], p1[0]), mxb = max3f(p0[2], p0[3], p1[1]); mxa = max3f(mxa, p1[2], p1[3]);
; #pragma unroll
;         for (int r = 4; r < 16; r += 4) { mxa = max3f(mxa, p0[r], p0[r + 1]); mxb = max3f(mxb, p0[r + 2], p0[r + 3]); mxa = max3f(mxa, p1[r], p1[r + 1]); mxb = max3f(mxb, p1[r + 2], p1[r + 3]); }
;         float mx = fmaxf(mxa, mxb);
;         if (__any(mx > 8.f)) {
;             mx = fmaxf(mx, __shfl_xor(mx, 32));
;             const float dl = fmaxf(mx, 0.f); mhat += dl;
;             const float f = __builtin_amdgcn_exp2f(-dl);
; #pragma unroll
;             for (int r = 0; r < 16; ++r) { p0[r] -= dl; p1[r] -= dl; negm[r] = -mhat; }
;             l *= f;
; #pragma unroll
;             for (int d = 0; d < NDT; ++d)
; #pragma unroll
;                 for (int r = 0; r < 16; ++r) o[d][r] *= f;
;         }
.Lcb1_j:
	v_max3_f32 v82, v156, v157, v98
	v_max3_f32 v83, v160, v161, v99
	v_max3_f32 v82, v82, v152, v153
	v_max3_f32 v83, v83, v166, v167
	v_max3_f32 v82, v82, v164, v165
	v_max3_f32 v83, v83, v154, v155
	v_max3_f32 v82, v82, v102, v103
	v_max3_f32 v83, v83, v162, v163
	v_max3_f32 v82, v82, v158, v159
	v_max3_f32 v83, v83, v104, v105
	v_max3_f32 v82, v82, v100, v101
	v_max3_f32 v83, v83, v112, v113
	v_max3_f32 v82, v82, v110, v111
	v_max3_f32 v83, v83, v108, v109
	v_max3_f32 v82, v82, v106, v107
	v_max_f32_e32 v82, v82, v83
	v_cmp_gt_f32_e32 vcc, 0xc3400000, v82
	s_cmp_eq_u64 vcc, exec
	s_cbranch_scc1 .Lsk1_p4a1
	v_cmp_lt_f32_e32 vcc, s52, v82
	s_cbranch_vccz .LBB0_580
	v_and_b32_e32 v67, 64, v170
	v_xor_b32_e32 v66, 32, v170
	v_add_u32_e32 v67, 64, v67
	v_cmp_lt_i32_e32 vcc, v66, v67
	s_nop 1
	v_cndmask_b32_e32 v66, v170, v66, vcc
	v_lshlrev_b32_e32 v66, 2, v66
	ds_bpermute_b32 v66, v66, v82
	s_waitcnt lgkmcnt(0)
	v_max3_f32 v67, v82, v66, 0
	v_exp_f32_e64 v66, -v67
	v_add_f32_e32 v176, v176, v67
	v_xor_b32_e32 v82, 0x80000000, v176
	v_sub_f32_e32 v98, v98, v67
	v_sub_f32_e32 v99, v99, v67
	v_sub_f32_e32 v152, v152, v67
	v_sub_f32_e32 v153, v153, v67
	v_sub_f32_e32 v102, v102, v67
	v_sub_f32_e32 v103, v103, v67
	v_sub_f32_e32 v154, v154, v67
	v_sub_f32_e32 v155, v155, v67
	v_sub_f32_e32 v100, v100, v67
	v_sub_f32_e32 v101, v101, v67
	v_sub_f32_e32 v104, v104, v67
	v_sub_f32_e32 v105, v105, v67
	v_sub_f32_e32 v106, v106, v67
	v_sub_f32_e32 v107, v107, v67
	v_sub_f32_e32 v108, v108, v67
	v_sub_f32_e32 v109, v109, v67
	v_pk_mul_f32 v[64:65], v[64:65], v[66:67] op_sel_hi:[1,0]
	v_pk_mul_f32 v[62:63], v[62:63], v[66:67] op_sel_hi:[1,0]
	v_pk_mul_f32 v[60:61], v[60:61], v[66:67] op_sel_hi:[1,0]
	v_pk_mul_f32 v[58:59], v[58:59], v[66:67] op_sel_hi:[1,0]
	v_pk_mul_f32 v[56:57], v[56:57], v[66:67] op_sel_hi:[1,0]
	v_pk_mul_f32 v[54:55], v[54:55], v[66:67] op_sel_hi:[1,0]
	v_pk_mul_f32 v[52:53], v[52:53], v[66:67] op_sel_hi:[1,0]
	v_pk_mul_f32 v[50:51], v[50:51], v[66:67] op_sel_hi:[1,0]
	v_pk_mul_f32 v[48:49], v[48:49], v[66:67] op_sel_hi:[1,0]
	v_pk_mul_f32 v[46:47], v[46:47], v[66:67] op_sel_hi:[1,0]
	v_pk_mul_f32 v[44:45], v[44:45], v[66:67] op_sel_hi:[1,0]
	v_pk_mul_f32 v[42:43], v[42:43], v[66:67] op_sel_hi:[1,0]
	v_pk_mul_f32 v[40:41], v[40:41], v[66:67] op_sel_hi:[1,0]
	v_pk_mul_f32 v[38:39], v[38:39], v[66:67] op_sel_hi:[1,0]
	v_pk_mul_f32 v[36:37], v[36:37], v[66:67] op_sel_hi:[1,0]
	v_pk_mul_f32 v[34:35], v[34:35], v[66:67] op_sel_hi:[1,0]
	v_pk_mul_f32 v[32:33], v[32:33], v[66:67] op_sel_hi:[1,0]
	v_pk_mul_f32 v[30:31], v[30:31], v[66:67] op_sel_hi:[1,0]
	v_pk_mul_f32 v[28:29], v[28:29], v[66:67] op_sel_hi:[1,0]
	v_pk_mul_f32 v[26:27], v[26:27], v[66:67] op_sel_hi:[1,0]
	v_pk_mul_f32 v[24:25], v[24:25], v[66:67] op_sel_hi:[1,0]
	v_pk_mul_f32 v[22:23], v[22:23], v[66:67] op_sel_hi:[1,0]
	v_pk_mul_f32 v[20:21], v[20:21], v[66:67] op_sel_hi:[1,0]
	v_pk_mul_f32 v[18:19], v[18:19], v[66:67] op_sel_hi:[1,0]
	v_pk_mul_f32 v[16:17], v[16:17], v[66:67] op_sel_hi:[1,0]
	v_pk_mul_f32 v[14:15], v[14:15], v[66:67] op_sel_hi:[1,0]
	v_pk_mul_f32 v[12:13], v[12:13], v[66:67] op_sel_hi:[1,0]
	v_pk_mul_f32 v[10:11], v[10:11], v[66:67] op_sel_hi:[1,0]
	v_pk_mul_f32 v[8:9], v[8:9], v[66:67] op_sel_hi:[1,0]
	v_pk_mul_f32 v[6:7], v[6:7], v[66:67] op_sel_hi:[1,0]
	v_pk_mul_f32 v[4:5], v[4:5], v[66:67] op_sel_hi:[1,0]
	v_pk_mul_f32 v[2:3], v[2:3], v[66:67] op_sel_hi:[1,0]
	v_sub_f32_e32 v156, v156, v67
	v_sub_f32_e32 v157, v157, v67
	v_sub_f32_e32 v160, v160, v67
	v_sub_f32_e32 v161, v161, v67
	v_sub_f32_e32 v164, v164, v67
	v_sub_f32_e32 v165, v165, v67
	v_sub_f32_e32 v166, v166, v67
	v_sub_f32_e32 v167, v167, v67
	v_sub_f32_e32 v158, v158, v67
	v_sub_f32_e32 v159, v159, v67
	v_sub_f32_e32 v162, v162, v67
	v_sub_f32_e32 v163, v163, v67
	v_sub_f32_e32 v110, v110, v67
	v_sub_f32_e32 v111, v111, v67
	v_sub_f32_e32 v112, v112, v67
	v_sub_f32_e32 v113, v113, v67
	v_mul_f32_e32 v151, v151, v66
	v_mov_b32_e32 v250, v82
	v_fmamk_f32 v66, v251, 0x00000000, v250
	v_fmamk_f32 v67, v251, 0x3f800000, v250
	v_fmamk_f32 v68, v251, 0x40000000, v250
	v_fmamk_f32 v69, v251, 0x40400000, v250
	v_fmamk_f32 v70, v251, 0x41000000, v250
	v_fmamk_f32 v71, v251, 0x41100000, v250
	v_fmamk_f32 v72, v251, 0x41200000, v250
	v_fmamk_f32 v73, v251, 0x41300000, v250
	v_fmamk_f32 v74, v251, 0x41800000, v250
	v_fmamk_f32 v75, v251, 0x41880000, v250
	v_fmamk_f32 v76, v251, 0x41900000, v250
	v_fmamk_f32 v77, v251, 0x41980000, v250
	v_fmamk_f32 v78, v251, 0x41c00000, v250
	v_fmamk_f32 v79, v251, 0x41c80000, v250
	v_fmamk_f32 v80, v251, 0x41d00000, v250
	v_fmamk_f32 v81, v251, 0x41d80000, v250
	v_fmamk_f32 v234, v251, 0x42000000, v250
	v_fmamk_f32 v235, v251, 0x42040000, v250
	v_fmamk_f32 v236, v251, 0x42080000, v250
	v_fmamk_f32 v237, v251, 0x420c0000, v250
	v_fmamk_f32 v238, v251, 0x42200000, v250
	v_fmamk_f32 v239, v251, 0x42240000, v250
	v_fmamk_f32 v240, v251, 0x42280000, v250
	v_fmamk_f32 v241, v251, 0x422c0000, v250
	v_fmamk_f32 v242, v251, 0x42400000, v250
	v_fmamk_f32 v243, v251, 0x42440000, v250
	v_fmamk_f32 v244, v251, 0x42480000, v250
	v_fmamk_f32 v245, v251, 0x424c0000, v250
	v_fmamk_f32 v246, v251, 0x42600000, v250
	v_fmamk_f32 v247, v251, 0x42640000, v250
	v_fmamk_f32 v248, v251, 0x42680000, v250
	v_fmamk_f32 v249, v251, 0x426c0000, v250
	s_branch .LBB0_581

; #define LAS __attribute__((address_space(3)))
; template <int DQK, int DV, bool BIAS> ...
;     ...
;     for (int g = 0; g < NG; ++g) {
;         const int pair = g & 1;
;         __syncthreads();
;         if (g + 1 < NG) {
; #pragma unroll
;             for (int j = 0; j < TPB; ++j) ATT_STORE((pair ^ 1) * TPB + j, j);
;             if (g + 2 < NG) {
; #pragma unroll
;                 for (int j = 0; j < TPB; ++j) ATT_LOAD((g + 2) * TPB + j, j);
;             }
;         }
; #pragma unroll
;       for (int sub = 0; sub < TPB; ++sub) {
;         const int t = g * TPB + sub, buf = pair * TPB + sub, vcur = buf;
;         f32x16 p0, p1;
;         const LAS unsigned char* kb = lds + buf * KBUF + r32 * KP + hi * 16;
; #pragma unroll
;         for (int ks = 0; ks < NKS; ++ks) {
;             const bf16x8 k0 = *(const LAS bf16x8*)(kb + ks * 32), k1 = *(const LAS bf16x8*)(kb + 32 * KP + ks * 32);
;             if (ks == 0) { p0 = __builtin_amdgcn_mfma_f32_32x32x16_bf16(k0, qf[0], negm, 0, 0, 0); p1 = __builtin_amdgcn_mfma_f32_32x32x16_bf16(k1, qf[0], negm, 0, 0, 0); }
;             else { p0 = __builtin_amdgcn_mfma_f32_32x32x16_bf16(k0, qf[ks], p0, 0, 0, 0); p1 = __builtin_amdgcn_mfma_f32_32x32x16_bf16(k1, qf[ks], p1, 0, 0, 0); }
;         }
;         if (BIAS) {
;             asm volatile("s_nop 15\n\ts_nop 7" : "+v"(p0), "+v"(p1));
;             const float d0 = qp - (float)(t * 64 + 4 * hi);
; #pragma unroll
;             for (int r = 0; r < 16; ++r) { const float dk = d0 - (float)((r & 3) + 8 * (r >> 2)); p0[r] = p0[r] - sl2 * fabsf(dk); p1[r] = p1[r] - sl2 * fabsf(dk - 32.f); }
;         } else {
;             asm volatile("s_nop 15\n\ts_nop 7" : "+v"(p0), "+v"(p1));
;     ...
;             float ls = 0.f;
; #pragma unroll
;             for (int hs = 0; hs < 4; ++hs) {
;                 float e[8];
; #pragma unroll
;                 for (int j = 0; j < 8; ++j) { e[j] = __builtin_amdgcn_exp2f(hs < 2 ? p0[8 * (hs & 1) + j] : p1[8 * (hs & 1) + j]); ls += e[j]; }
;                 pw[hs].x = cvtpk(e[0], e[1]); pw[hs].y = cvtpk(e[2], e[3]); pw[hs].z = cvtpk(e[4], e[5]); pw[hs].w = cvtpk(e[6], e[7]);
;                 const bf16x8 pbv = __builtin_bit_cast(bf16x8, pw[hs]);
; #pragma unroll
;                 for (int d = 0; d < NDT; ++d) { const LAS unsigned char* vp = vbase + d * 4096 + hs * 1024;
.LBB0_584:
	s_add_i32 s100, s51, 1
	s_cmp_lt_u32 s100, s96
	s_cselect_b32 s101, 1, 2
	s_cmp_eq_u32 s100, s96
	s_cselect_b32 s101, 0, s101
	s_cmp_eq_u32 s101, s97
	s_cbranch_scc1 .Lcb2_ok
	s_mov_b32 s97, s101
	s_cmp_eq_u32 s101, 1
	s_cselect_b32 s100, 0x3f800000, 0xbf800000
	s_cmp_eq_u32 s101, 0
	s_cselect_b32 s100, 0, s100
	v_mul_f32_e32 v251, s100, v142
	v_fmamk_f32 v66, v251, 0x00000000, v250
	v_fmamk_f32 v67, v251, 0x3f800000, v250
	v_fmamk_f32 v68, v251, 0x40000000, v250
	v_fmamk_f32 v69, v251, 0x40400000, v250
	v_fmamk_f32 v70, v251, 0x41000000, v250
	v_fmamk_f32 v71, v251, 0x41100000, v250
	v_fmamk_f32 v72, v251, 0x41200000, v250
	v_fmamk_f32 v73, v251, 0x41300000, v250
	v_fmamk_f32 v74, v251, 0x41800000, v250
	v_fmamk_f32 v75, v251, 0x41880000, v250
	v_fmamk_f32 v76, v251, 0x41900000, v250
	v_fmamk_f32 v77, v251, 0x41980000, v250
	v_fmamk_f32 v78, v251, 0x41c00000, v250
	v_fmamk_f32 v79, v251, 0x41c80000, v250
	v_fmamk_f32 v80, v251, 0x41d00000, v250
	v_fmamk_f32 v81, v251, 0x41d80000, v250
	v_fmamk_f32 v234, v251, 0x42000000, v250
	v_fmamk_f32 v235, v251, 0x42040000, v250
	v_fmamk_f32 v236, v251, 0x42080000, v250
	v_fmamk_f32 v237, v251, 0x420c0000, v250
	v_fmamk_f32 v238, v251, 0x42200000, v250
	v_fmamk_f32 v239, v251, 0x42240000, v250
	v_fmamk_f32 v240, v251, 0x42280000, v250
	v_fmamk_f32 v241, v251, 0x422c0000, v250
	v_fmamk_f32 v242, v251, 0x42400000, v250
	v_fmamk_f32 v243, v251, 0x42440000, v250
	v_fmamk_f32 v244, v251, 0x42480000, v250
	v_fmamk_f32 v245, v251, 0x424c0000, v250
	v_fmamk_f32 v246, v251, 0x42600000, v250
	v_fmamk_f32 v247, v251, 0x42640000, v250
	v_fmamk_f32 v248, v251, 0x42680000, v250
	v_fmamk_f32 v249, v251, 0x426c0000, v250
	s_nop 1
.Lcb2_ok:
	ds_read_b128 v[192:195], v175 offset:9216
	ds_read_b128 v[196:199], v175 offset:9248
	v_add_f32_e32 v156, v157, v156
	v_add_f32_e32 v156, v160, v156
	s_waitcnt lgkmcnt(1)
	v_mfma_f32_32x32x16_bf16 v[98:113], v[192:195], v[114:117], v[66:81]
	ds_read_b128 v[192:195], v175 offset:13824
	ds_read_b128 v[200:203], v175 offset:13856
	v_add_f32_e32 v156, v161, v156
	v_add_f32_e32 v156, v164, v156
	v_add_f32_e32 v150, v150, v156
	v_add_f32_e32 v150, v165, v150
	v_add_f32_e32 v150, v166, v150
	v_add_f32_e32 v150, v167, v150
	s_waitcnt lgkmcnt(1)
	v_mfma_f32_32x32x16_bf16 v[82:97], v[192:195], v[114:117], v[234:249]
	v_add_f32_e32 v150, v177, v150
	v_add_f32_e32 v150, v178, v150
	v_add_f32_e32 v150, v158, v150
	v_add_f32_e32 v150, v159, v150
	ds_read_b128 v[164:167], v175 offset:9280
	v_add_f32_e32 v150, v162, v150
	v_add_f32_e32 v150, v163, v150
	v_mfma_f32_32x32x16_bf16 v[98:113], v[196:199], v[118:121], v[98:113]
	v_add_f32_e32 v150, v179, v150
	v_add_f32_e32 v150, v180, v150
	v_add_f32_e32 v150, v181, v150
	v_add_f32_e32 v150, v152, v150
	ds_read_b128 v[156:159], v175 offset:13888
	ds_read_b128 v[160:163], v175 offset:9312
	v_add_f32_e32 v150, v153, v150
	v_add_f32_e32 v150, v182, v150
	s_waitcnt lgkmcnt(3)
	v_mfma_f32_32x32x16_bf16 v[82:97], v[200:203], v[118:121], v[82:97]
	v_add_f32_e32 v150, v183, v150
	v_add_f32_e32 v150, v154, v150
	v_add_f32_e32 v150, v155, v150
	v_add_f32_e32 v150, v184, v150
	v_add_f32_e32 v150, v185, v150
	v_add_u32_e32 v152, 64, v173
	v_add_f32_e32 v150, v186, v150
	s_waitcnt lgkmcnt(2)
	v_mfma_f32_32x32x16_bf16 v[98:113], v[164:167], v[122:125], v[98:113]
	ds_read_b128 v[164:167], v175 offset:13920
	v_cvt_f32_u32_e32 v152, v152
	v_add_f32_e32 v150, v187, v150
	v_add_f32_e32 v150, v188, v150
	v_add_f32_e32 v150, v191, v150
	v_add_f32_e32 v150, v189, v150
	v_add_f32_e32 v150, v190, v150
	s_waitcnt lgkmcnt(2)
	v_mfma_f32_32x32x16_bf16 v[82:97], v[156:159], v[122:125], v[82:97]
	v_add_f32_e32 v158, v151, v150
	s_waitcnt lgkmcnt(1)
	v_mfma_f32_32x32x16_bf16 v[98:113], v[160:163], v[126:129], v[98:113]
	v_sub_f32_e32 v160, v172, v152
	v_add_f32_e32 v161, -1.0, v160
	s_waitcnt lgkmcnt(0)
	v_mfma_f32_32x32x16_bf16 v[82:97], v[164:167], v[126:129], v[82:97]
	s_nop 15
	s_nop 7
	s_nop 5
	s_add_i32 s100, s51, 1
	s_cmp_eq_u32 s100, s96
	s_cbranch_scc1 .Lcb2_d
	v_mul_f32_e64 v252, -v251, v160
	v_add_f32_e32 v150, v252, v98
	v_add_f32_e32 v151, v252, v99
	v_add_f32_e32 v83, v252, v83
	v_add_f32_e32 v82, v252, v82
	v_add_f32_e32 v153, v252, v101
	v_add_f32_e32 v152, v252, v100
	v_add_f32_e32 v99, v252, v85
	v_add_f32_e32 v98, v252, v84
	v_add_f32_e32 v155, v252, v103
	v_add_f32_e32 v154, v252, v102
	v_add_f32_e32 v101, v252, v87
	v_add_f32_e32 v100, v252, v86
	v_add_f32_e32 v157, v252, v105
	v_add_f32_e32 v156, v252, v104
	v_add_f32_e32 v103, v252, v89
	v_add_f32_e32 v102, v252, v88
	v_add_f32_e32 v105, v252, v107
	v_add_f32_e32 v104, v252, v106
	v_add_f32_e32 v107, v252, v109
	v_add_f32_e32 v106, v252, v108
	v_add_f32_e32 v85, v252, v91
	v_add_f32_e32 v84, v252, v90
	v_add_f32_e32 v87, v252, v93
	v_add_f32_e32 v86, v252, v92
	v_add_f32_e32 v93, v252, v111
	v_add_f32_e32 v92, v252, v110
	v_add_f32_e32 v89, v252, v95
	v_add_f32_e32 v88, v252, v94
	v_add_f32_e32 v95, v252, v113
	v_add_f32_e32 v94, v252, v112
	v_add_f32_e32 v91, v252, v97
	v_add_f32_e32 v90, v252, v96
	s_branch .Lcb2_j
; template <int DQK, int DV, bool BIAS> ...
;     ...
;         if (BIAS) {
;             asm volatile("s_nop 15\n\ts_nop 7" : "+v"(p0), "+v"(p1));
;             const float d0 = qp - (float)(t * 64 + 4 * hi);
; #pragma unroll
;             for (int r = 0; r < 16; ++r) { const float dk = d0 - (float)((r & 3) + 8 * (r >> 2)); p0[r] = p0[r] - sl2 * fabsf(dk); p1[r] = p1[r] - sl2 * fabsf(dk - 32.f); }
.Lcb2_d:
	v_fma_f32 v150, -v142, |v160|, v98
	v_fma_f32 v151, -v143, |v161|, v99
	v_pk_add_f32 v[98:99], v[160:161], s[8:9] op_sel_hi:[1,0]
	s_nop 0
	v_fma_f32 v83, -v143, |v99|, v83
	v_fma_f32 v82, -v142, |v98|, v82
	s_nop 0
	v_pk_add_f32 v[98:99], v[160:161], s[10:11] op_sel_hi:[0,1]
	v_fma_f32 v153, -v143, |v99|, v101
	v_fma_f32 v152, -v142, |v98|, v100
	v_pk_add_f32 v[98:99], v[98:99], s[8:9] op_sel_hi:[1,0]
	v_fma_f32 v99, -v143, |v99|, v85
	v_fma_f32 v98, -v142, |v98|, v84
	v_pk_add_f32 v[84:85], v[160:161], s[22:23] op_sel_hi:[0,1]
	v_fma_f32 v155, -v143, |v85|, v103
	v_fma_f32 v154, -v142, |v84|, v102
	v_pk_add_f32 v[84:85], v[84:85], s[8:9] op_sel_hi:[1,0]
	v_fma_f32 v101, -v143, |v85|, v87
	v_fma_f32 v100, -v142, |v84|, v86
	v_pk_add_f32 v[84:85], v[160:161], s[34:35] op_sel_hi:[0,1]
	v_fma_f32 v157, -v143, |v85|, v105
	v_fma_f32 v156, -v142, |v84|, v104
	v_pk_add_f32 v[84:85], v[84:85], s[8:9] op_sel_hi:[1,0]
	v_fma_f32 v103, -v143, |v85|, v89
	v_fma_f32 v102, -v142, |v84|, v88
	v_pk_add_f32 v[84:85], v[160:161], s[36:37] op_sel_hi:[0,1]
	v_fma_f32 v105, -v143, |v85|, v107
	v_fma_f32 v104, -v142, |v84|, v106
	v_pk_add_f32 v[86:87], v[160:161], s[38:39] op_sel_hi:[0,1]
	v_pk_add_f32 v[84:85], v[84:85], s[8:9] op_sel_hi:[1,0]
	v_fma_f32 v107, -v143, |v87|, v109
	v_fma_f32 v106, -v142, |v86|, v108
	v_fma_f32 v85, -v143, |v85|, v91
	v_fma_f32 v84, -v142, |v84|, v90
	v_pk_add_f32 v[86:87], v[86:87], s[8:9] op_sel_hi:[1,0]
	v_pk_add_f32 v[88:89], v[160:161], s[40:41] op_sel_hi:[0,1]
	v_fma_f32 v87, -v143, |v87|, v93
	v_fma_f32 v86, -v142, |v86|, v92
	v_fma_f32 v93, -v143, |v89|, v111
	v_fma_f32 v92, -v142, |v88|, v110
	v_pk_add_f32 v[88:89], v[88:89], s[8:9] op_sel_hi:[1,0]
	v_fma_f32 v89, -v143, |v89|, v95
	v_fma_f32 v88, -v142, |v88|, v94
	v_pk_add_f32 v[90:91], v[160:161], s[42:43] op_sel_hi:[0,1]
	v_fma_f32 v95, -v143, |v91|, v113
	v_fma_f32 v94, -v142, |v90|, v112
	v_pk_add_f32 v[90:91], v[90:91], s[8:9] op_sel_hi:[1,0]
	v_fma_f32 v91, -v143, |v91|, v97
	v_fma_f32 v90, -v142, |v90|, v96
; __device__ __forceinline__ float max3f(float a, float b, float c) { float r; asm("v_max3_f32 %0, %1, %2, %3" : "=v"(r) : "v"(a), "v"(b), "v"(c)); return r; }
; template <int DQK, int DV, bool BIAS> ...
;     ...
;         float mxa = max3f(p0[0], p0[1], p1[0]), mxb = max3f(p0[2], p0[3], p1[1]); mxa = max3f(mxa, p1[2], p1[3]);
; #pragma unroll
;         for (int r = 4; r < 16; r += 4) { mxa = max3f(mxa, p0[r], p0[r + 1]); mxb = max3f(mxb, p0[r + 2], p0[r + 3]); mxa = max3f(mxa, p1[r], p1[r + 1]); mxb = max3f(mxb, p1[r + 2], p1[r + 3]); }
;         float mx = fmaxf(mxa, mxb);
;         if (__any(mx > 8.f)) {
;             mx = fmaxf(mx, __shfl_xor(mx, 32));
;             const float dl = fmaxf(mx, 0.f); mhat += dl;
;             const float f = __builtin_amdgcn_exp2f(-dl);
; #pragma unroll
;             for (int r = 0; r < 16; ++r) { p0[r] -= dl; p1[r] -= dl; negm[r] = -mhat; }
;             l *= f;
; #pragma unroll
;             for (int d = 0; d < NDT; ++d)
; #pragma unroll
;                 for (int r = 0; r < 16; ++r) o[d][r] *= f;
;         }
.Lcb2_j:
	v_max3_f32 v96, v150, v151, v82
	v_max3_f32 v97, v152, v153, v83
	v_max3_f32 v96, v96, v98, v99
	v_max3_f32 v97, v97, v156, v157
	v_max3_f32 v96, v96, v154, v155
	v_max3_f32 v97, v97, v102, v103
	v_max3_f32 v96, v96, v100, v101
	v_max3_f32 v97, v97, v106, v107
	v_max3_f32 v96, v96, v104, v105
	v_max3_f32 v97, v97, v86, v87
	v_max3_f32 v96, v96, v84, v85
	v_max3_f32 v97, v97, v94, v95
	v_max3_f32 v96, v96, v92, v93
	v_max3_f32 v97, v97, v90, v91
	v_max3_f32 v96, v96, v88, v89
	v_max_f32_e32 v96, v96, v97
	v_cmp_gt_f32_e32 vcc, 0xc3400000, v96
	s_cmp_eq_u64 vcc, exec
	s_cbranch_scc1 .Lsk2_p4a1
	v_cmp_lt_f32_e32 vcc, s52, v96
	s_cbranch_vccz .LBB0_575
	v_and_b32_e32 v67, 64, v170
	v_xor_b32_e32 v66, 32, v170
	v_add_u32_e32 v67, 64, v67
	v_cmp_lt_i32_e32 vcc, v66, v67
	s_nop 1
	v_cndmask_b32_e32 v66, v170, v66, vcc
	v_lshlrev_b32_e32 v66, 2, v66
	ds_bpermute_b32 v66, v66, v96
	s_waitcnt lgkmcnt(0)
	v_max3_f32 v67, v96, v66, 0
	v_exp_f32_e64 v68, -v67
	v_add_f32_e32 v176, v176, v67
	v_xor_b32_e32 v66, 0x80000000, v176
	v_sub_f32_e32 v82, v82, v67
	v_sub_f32_e32 v83, v83, v67
	v_sub_f32_e32 v98, v98, v67
	v_sub_f32_e32 v99, v99, v67
	v_sub_f32_e32 v100, v100, v67
	v_sub_f32_e32 v101, v101, v67
	v_sub_f32_e32 v102, v102, v67
	v_sub_f32_e32 v103, v103, v67
	v_sub_f32_e32 v84, v84, v67
	v_sub_f32_e32 v85, v85, v67
	v_sub_f32_e32 v86, v86, v67
	v_sub_f32_e32 v87, v87, v67
	v_sub_f32_e32 v88, v88, v67
	v_sub_f32_e32 v89, v89, v67
	v_sub_f32_e32 v90, v90, v67
	v_sub_f32_e32 v91, v91, v67
	v_pk_mul_f32 v[64:65], v[64:65], v[68:69] op_sel_hi:[1,0]
	v_pk_mul_f32 v[62:63], v[62:63], v[68:69] op_sel_hi:[1,0]
	v_pk_mul_f32 v[60:61], v[60:61], v[68:69] op_sel_hi:[1,0]
	v_pk_mul_f32 v[58:59], v[58:59], v[68:69] op_sel_hi:[1,0]
	v_pk_mul_f32 v[56:57], v[56:57], v[68:69] op_sel_hi:[1,0]
	v_pk_mul_f32 v[54:55], v[54:55], v[68:69] op_sel_hi:[1,0]
	v_pk_mul_f32 v[52:53], v[52:53], v[68:69] op_sel_hi:[1,0]
	v_pk_mul_f32 v[50:51], v[50:51], v[68:69] op_sel_hi:[1,0]
	v_pk_mul_f32 v[48:49], v[48:49], v[68:69] op_sel_hi:[1,0]
	v_pk_mul_f32 v[46:47], v[46:47], v[68:69] op_sel_hi:[1,0]
	v_pk_mul_f32 v[44:45], v[44:45], v[68:69] op_sel_hi:[1,0]
	v_pk_mul_f32 v[42:43], v[42:43], v[68:69] op_sel_hi:[1,0]
	v_pk_mul_f32 v[40:41], v[40:41], v[68:69] op_sel_hi:[1,0]
	v_pk_mul_f32 v[38:39], v[38:39], v[68:69] op_sel_hi:[1,0]
	v_pk_mul_f32 v[36:37], v[36:37], v[68:69] op_sel_hi:[1,0]
	v_pk_mul_f32 v[34:35], v[34:35], v[68:69] op_sel_hi:[1,0]
	v_pk_mul_f32 v[32:33], v[32:33], v[68:69] op_sel_hi:[1,0]
	v_pk_mul_f32 v[30:31], v[30:31], v[68:69] op_sel_hi:[1,0]
	v_pk_mul_f32 v[28:29], v[28:29], v[68:69] op_sel_hi:[1,0]
	v_pk_mul_f32 v[26:27], v[26:27], v[68:69] op_sel_hi:[1,0]
	v_pk_mul_f32 v[24:25], v[24:25], v[68:69] op_sel_hi:[1,0]
	v_pk_mul_f32 v[22:23], v[22:23], v[68:69] op_sel_hi:[1,0]
	v_pk_mul_f32 v[20:21], v[20:21], v[68:69] op_sel_hi:[1,0]
	v_pk_mul_f32 v[18:19], v[18:19], v[68:69] op_sel_hi:[1,0]
	v_pk_mul_f32 v[16:17], v[16:17], v[68:69] op_sel_hi:[1,0]
	v_pk_mul_f32 v[14:15], v[14:15], v[68:69] op_sel_hi:[1,0]
	v_pk_mul_f32 v[12:13], v[12:13], v[68:69] op_sel_hi:[1,0]
	v_pk_mul_f32 v[10:11], v[10:11], v[68:69] op_sel_hi:[1,0]
	v_pk_mul_f32 v[8:9], v[8:9], v[68:69] op_sel_hi:[1,0]
	v_pk_mul_f32 v[6:7], v[6:7], v[68:69] op_sel_hi:[1,0]
	v_pk_mul_f32 v[4:5], v[4:5], v[68:69] op_sel_hi:[1,0]
	v_pk_mul_f32 v[2:3], v[2:3], v[68:69] op_sel_hi:[1,0]
	v_sub_f32_e32 v150, v150, v67
	v_sub_f32_e32 v151, v151, v67
	v_sub_f32_e32 v152, v152, v67
	v_sub_f32_e32 v153, v153, v67
	v_sub_f32_e32 v154, v154, v67
	v_sub_f32_e32 v155, v155, v67
	v_sub_f32_e32 v156, v156, v67
	v_sub_f32_e32 v157, v157, v67
	v_sub_f32_e32 v104, v104, v67
	v_sub_f32_e32 v105, v105, v67
	v_sub_f32_e32 v106, v106, v67
	v_sub_f32_e32 v107, v107, v67
	v_sub_f32_e32 v92, v92, v67
	v_sub_f32_e32 v93, v93, v67
	v_sub_f32_e32 v94, v94, v67
	v_sub_f32_e32 v95, v95, v67
	v_mul_f32_e32 v158, v158, v68
	v_mov_b32_e32 v250, v66
	v_fmamk_f32 v66, v251, 0x00000000, v250
	v_fmamk_f32 v67, v251, 0x3f800000, v250
	v_fmamk_f32 v68, v251, 0x40000000, v250
	v_fmamk_f32 v69, v251, 0x40400000, v250
	v_fmamk_f32 v70, v251, 0x41000000, v250
	v_fmamk_f32 v71, v251, 0x41100000, v250
	v_fmamk_f32 v72, v251, 0x41200000, v250
	v_fmamk_f32 v73, v251, 0x41300000, v250
	v_fmamk_f32 v74, v251, 0x41800000, v250
	v_fmamk_f32 v75, v251, 0x41880000, v250
	v_fmamk_f32 v76, v251, 0x41900000, v250
	v_fmamk_f32 v77, v251, 0x41980000, v250
	v_fmamk_f32 v78, v251, 0x41c00000, v250
	v_fmamk_f32 v79, v251, 0x41c80000, v250
	v_fmamk_f32 v80, v251, 0x41d00000, v250
	v_fmamk_f32 v81, v251, 0x41d80000, v250
	v_fmamk_f32 v234, v251, 0x42000000, v250
	v_fmamk_f32 v235, v251, 0x42040000, v250
	v_fmamk_f32 v236, v251, 0x42080000, v250
	v_fmamk_f32 v237, v251, 0x420c0000, v250
	v_fmamk_f32 v238, v251, 0x42200000, v250
	v_fmamk_f32 v239, v251, 0x42240000, v250
	v_fmamk_f32 v240, v251, 0x42280000, v250
	v_fmamk_f32 v241, v251, 0x422c0000, v250
	v_fmamk_f32 v242, v251, 0x42400000, v250
	v_fmamk_f32 v243, v251, 0x42440000, v250
	v_fmamk_f32 v244, v251, 0x42480000, v250
	v_fmamk_f32 v245, v251, 0x424c0000, v250
	v_fmamk_f32 v246, v251, 0x42600000, v250
	v_fmamk_f32 v247, v251, 0x42640000, v250
	v_fmamk_f32 v248, v251, 0x42680000, v250
	v_fmamk_f32 v249, v251, 0x426c0000, v250
	s_branch .LBB0_575

; template <int DQK, int DV, bool BIAS> ...
;     ...
;     for (int ks = 0; ks < NKS; ++ks) qf[ks] = ks < 4 ? *(const bf16x8*)(Qw + (size_t)r32 * ldq + ks * 16 + hi * 8) : *(const bf16x8*)(Q2w + (size_t)r32 * ldq2 + (ks - 4) * 16 + hi * 8);
; #pragma unroll
;     for (int ks = 0; ks < 4; ++ks) qf[ks] = scale_frag(qf[ks], cs);
;     if constexpr (DQK == 96) {
;         const float* rp = ropetab + ((size_t)(qpos0 + r32) * 16) * 2;
; #pragma unroll
;         for (int ks = 4; ks < 6; ++ks) {
;             const f32x4 c0 = *(const f32x4*)(rp + ((ks - 4) * 8 + hi * 4) * 2), c1 = *(const f32x4*)(rp + ((ks - 4) * 8 + hi * 4 + 2) * 2);
;             const u32x4 w = __builtin_bit_cast(u32x4, qf[ks]); u32x4 ow;
;     ...
;     l += __shfl_xor(l, 32);
;     const float inv = 1.f / l;
; #pragma unroll
;     for (int d = 0; d < NDT; ++d)
; #pragma unroll
;         for (int r = 0; r < 16; ++r) o[d][r] *= inv;
; }
; template <int NDT> __device__ __forceinline__ void attn_store(const f32x16 (&o)[NDT], bf16_t* Ow, int ldo, int r32, int hi) {
; #pragma unroll
;     for (int d = 0; d < NDT; ++d)
; #pragma unroll
;         for (int q = 0; q < 4; ++q) { u32x2 w; w.x = cvtpk(o[d][4 * q], o[d][4 * q + 1]); w.y = cvtpk(o[d][4 * q + 2], o[d][4 * q + 3]); *(u32x2*)(Ow + (size_t)r32 * ldo + 32 * d + 8 * q + 4 * hi) = w; }
; }
; __device__ __forceinline__ void attn_phase(PPtr P, int li, LAS unsigned char* lds, int vcu, int wave, int lane) {
;     bf16_t* proj = (bf16_t*)(P->ws + OFF_PROJ); bf16_t* mlaq = (bf16_t*)(P->ws + OFF_MLAQ); const bf16_t* mlakv = (const bf16_t*)(P->ws + OFF_MLAKV);
;     const int r32 = lane & 31, hi = lane >> 5;
;     {
;         const int b = vcu >> 6, h = (vcu >> 4) & 3, qb = vcu & 15;
;         const size_t seq0 = (size_t)b * SEQL, qrow = seq0 + qb * 256 + wave * 32;
;         const float slope = __builtin_amdgcn_exp2f(-2.f * (float)(h + 1));
;         f32x16 o1[4], o2[4];
;         attn_pass<64, 128, true>(lds, proj + qrow * LDP + C_AQ + h * 128, LDP, nullptr, 0, proj + seq0 * LDP + C_AK + h * 128, LDP, nullptr, 0, proj + seq0 * LDP + C_AV + h * 128, LDP, qb * 256 + wave * 32, 0.125f * LOG2E, slope * LOG2E, nullptr, o1);
;         LAS unsigned* o1s = (LAS unsigned*)(lds + 81920 + wave * 8192) + lane;
; #pragma unroll
;         for (int d = 0; d < 4; ++d)
; #pragma unroll
;             for (int r = 0; r < 8; ++r) o1s[(d * 8 + r) * 64] = cvtpk(o1[d][2 * r], o1[d][2 * r + 1]);
.LBB0_586:
	v_and_b32_e32 v67, 64, v170
	v_xor_b32_e32 v66, 32, v170
	v_add_u32_e32 v172, 64, v67
	v_cmp_lt_i32_e32 vcc, v66, v172
	v_and_b32_e32 v173, 63, v169
	s_nop 0
	v_cndmask_b32_e32 v66, v170, v66, vcc
	v_lshlrev_b32_e32 v168, 2, v66
	ds_bpermute_b32 v66, v168, v151
	s_barrier
	s_waitcnt lgkmcnt(0)
	s_movk_i32 s8, 0x1940
	s_mov_b32 s10, 0xc1000000
	v_add_f32_e32 v66, v151, v66
	v_div_scale_f32 v67, s[6:7], v66, v66, 1.0
	v_rcp_f32_e32 v68, v67
	s_lshl_b32 s6, s50, 13
	s_add_i32 s6, s6, 0
	v_mov_b32_e32 v151, 0
	v_fma_f32 v69, -v67, v68, 1.0
	v_fmac_f32_e32 v68, v69, v68
	v_div_scale_f32 v69, vcc, 1.0, v66, 1.0
	v_mul_f32_e32 v70, v69, v68
	v_fma_f32 v71, -v67, v70, v69
	v_fmac_f32_e32 v70, v71, v68
	v_fma_f32 v67, -v67, v70, v69
	v_div_fmas_f32 v67, v67, v68, v70
	v_div_fixup_f32 v66, v67, v66, 1.0
	v_pk_mul_f32 v[50:51], v[50:51], v[66:67] op_sel_hi:[1,0]
	v_pk_mul_f32 v[52:53], v[52:53], v[66:67] op_sel_hi:[1,0]
	v_pk_mul_f32 v[54:55], v[54:55], v[66:67] op_sel_hi:[1,0]
	v_pk_mul_f32 v[56:57], v[56:57], v[66:67] op_sel_hi:[1,0]
	v_pk_mul_f32 v[58:59], v[58:59], v[66:67] op_sel_hi:[1,0]
	v_pk_mul_f32 v[60:61], v[60:61], v[66:67] op_sel_hi:[1,0]
	v_pk_mul_f32 v[62:63], v[62:63], v[66:67] op_sel_hi:[1,0]
	v_pk_mul_f32 v[64:65], v[64:65], v[66:67] op_sel_hi:[1,0]
	v_pk_mul_f32 v[34:35], v[34:35], v[66:67] op_sel_hi:[1,0]
	v_pk_mul_f32 v[36:37], v[36:37], v[66:67] op_sel_hi:[1,0]
	v_pk_mul_f32 v[38:39], v[38:39], v[66:67] op_sel_hi:[1,0]
	v_pk_mul_f32 v[40:41], v[40:41], v[66:67] op_sel_hi:[1,0]
	v_pk_mul_f32 v[42:43], v[42:43], v[66:67] op_sel_hi:[1,0]
	v_pk_mul_f32 v[44:45], v[44:45], v[66:67] op_sel_hi:[1,0]
	v_pk_mul_f32 v[46:47], v[46:47], v[66:67] op_sel_hi:[1,0]
	v_pk_mul_f32 v[48:49], v[48:49], v[66:67] op_sel_hi:[1,0]
	v_pk_mul_f32 v[18:19], v[18:19], v[66:67] op_sel_hi:[1,0]
	v_pk_mul_f32 v[20:21], v[20:21], v[66:67] op_sel_hi:[1,0]
	v_pk_mul_f32 v[22:23], v[22:23], v[66:67] op_sel_hi:[1,0]
	v_pk_mul_f32 v[24:25], v[24:25], v[66:67] op_sel_hi:[1,0]
	v_pk_mul_f32 v[26:27], v[26:27], v[66:67] op_sel_hi:[1,0]
	v_pk_mul_f32 v[28:29], v[28:29], v[66:67] op_sel_hi:[1,0]
	v_pk_mul_f32 v[30:31], v[30:31], v[66:67] op_sel_hi:[1,0]
	v_pk_mul_f32 v[32:33], v[32:33], v[66:67] op_sel_hi:[1,0]
	v_pk_mul_f32 v[2:3], v[2:3], v[66:67] op_sel_hi:[1,0]
	v_pk_mul_f32 v[4:5], v[4:5], v[66:67] op_sel_hi:[1,0]
	v_pk_mul_f32 v[6:7], v[6:7], v[66:67] op_sel_hi:[1,0]
	v_pk_mul_f32 v[8:9], v[8:9], v[66:67] op_sel_hi:[1,0]
	v_pk_mul_f32 v[10:11], v[10:11], v[66:67] op_sel_hi:[1,0]
	v_pk_mul_f32 v[12:13], v[12:13], v[66:67] op_sel_hi:[1,0]
	v_pk_mul_f32 v[14:15], v[14:15], v[66:67] op_sel_hi:[1,0]
	v_pk_mul_f32 v[16:17], v[16:17], v[66:67] op_sel_hi:[1,0]
	v_lshl_add_u32 v66, v173, 2, s6
	v_add_u32_e32 v171, 0x14000, v66
	v_cvt_pk_bf16_f32 v50, v50, v51
	v_cvt_pk_bf16_f32 v51, v52, v53
	v_cvt_pk_bf16_f32 v34, v34, v35
	v_cvt_pk_bf16_f32 v35, v36, v37
	v_cvt_pk_bf16_f32 v18, v18, v19
	v_cvt_pk_bf16_f32 v19, v20, v21
	v_cvt_pk_bf16_f32 v2, v2, v3
	v_cvt_pk_bf16_f32 v3, v4, v5
	ds_write2st64_b32 v171, v50, v51 offset1:1
	v_cvt_pk_bf16_f32 v50, v54, v55
	v_cvt_pk_bf16_f32 v51, v56, v57
	ds_write2st64_b32 v171, v34, v35 offset0:8 offset1:9
	v_cvt_pk_bf16_f32 v34, v38, v39
	v_cvt_pk_bf16_f32 v35, v40, v41
	ds_write2st64_b32 v171, v18, v19 offset0:16 offset1:17
	v_cvt_pk_bf16_f32 v18, v22, v23
	v_cvt_pk_bf16_f32 v19, v24, v25
	ds_write2st64_b32 v171, v2, v3 offset0:24 offset1:25
	v_cvt_pk_bf16_f32 v2, v6, v7
	v_cvt_pk_bf16_f32 v3, v8, v9
	ds_write2st64_b32 v171, v50, v51 offset0:2 offset1:3
	v_cvt_pk_bf16_f32 v50, v58, v59
	v_cvt_pk_bf16_f32 v51, v60, v61
	ds_write2st64_b32 v171, v34, v35 offset0:10 offset1:11
	v_cvt_pk_bf16_f32 v34, v42, v43
	v_cvt_pk_bf16_f32 v35, v44, v45
	ds_write2st64_b32 v171, v18, v19 offset0:18 offset1:19
	v_cvt_pk_bf16_f32 v18, v26, v27
	v_cvt_pk_bf16_f32 v19, v28, v29
	ds_write2st64_b32 v171, v2, v3 offset0:26 offset1:27
	v_cvt_pk_bf16_f32 v2, v10, v11
	v_cvt_pk_bf16_f32 v3, v12, v13
	ds_write2st64_b32 v171, v50, v51 offset0:4 offset1:5
	v_cvt_pk_bf16_f32 v50, v62, v63
	v_cvt_pk_bf16_f32 v51, v64, v65
	ds_write2st64_b32 v171, v34, v35 offset0:12 offset1:13
	v_cvt_pk_bf16_f32 v34, v46, v47
	v_cvt_pk_bf16_f32 v35, v48, v49
	ds_write2st64_b32 v171, v18, v19 offset0:20 offset1:21
	v_cvt_pk_bf16_f32 v18, v30, v31
	v_cvt_pk_bf16_f32 v19, v32, v33
	ds_write2st64_b32 v171, v2, v3 offset0:28 offset1:29
	v_cvt_pk_bf16_f32 v2, v14, v15
	v_cvt_pk_bf16_f32 v3, v16, v17
	v_mov_b32_e32 v22, v1
	ds_write2st64_b32 v171, v50, v51 offset0:6 offset1:7
	ds_write2st64_b32 v171, v34, v35 offset0:14 offset1:15
	ds_write2st64_b32 v171, v18, v19 offset0:22 offset1:23
	ds_write2st64_b32 v171, v2, v3 offset0:30 offset1:31
	s_mov_b32 s6, 0x3e38aa3b
	v_and_b32_e32 v23, 31, v22
	v_mul_u32_u24_e32 v2, 0xca0, v23
	v_bfe_u32 v24, v22, 5, 1
	v_lshlrev_b32_e32 v150, 1, v2
	v_lshl_add_u64 v[2:3], s[18:19], 0, v[150:151]
	v_lshlrev_b32_e32 v150, 4, v24
	v_lshl_add_u64 v[18:19], v[2:3], 0, v[150:151]
	global_load_dwordx4 v[2:5], v[18:19], off offset:128
	global_load_dwordx4 v[6:9], v[18:19], off offset:160
	global_load_dwordx4 v[10:13], v[18:19], off offset:192
	global_load_dwordx4 v[14:17], v[18:19], off offset:224
	v_ashrrev_i32_e32 v25, 3, v22
	v_lshlrev_b32_e32 v26, 4, v22
	v_lshrrev_b32_e32 v28, 2, v22
	v_lshlrev_b32_e32 v177, 2, v24
	v_and_b32_e32 v29, 0xfc0, v26
	v_and_b32_e32 v30, 48, v26
	v_mov_b32_e32 v50, v151
	v_mov_b32_e32 v51, v151
	v_mov_b32_e32 v52, v151
	v_mov_b32_e32 v53, v151
	v_mov_b32_e32 v54, v151
	v_mov_b32_e32 v55, v151
	v_mov_b32_e32 v56, v151
	v_mov_b32_e32 v57, v151
	v_mov_b32_e32 v58, v151
	v_mov_b32_e32 v59, v151
	v_mov_b32_e32 v60, v151
	v_mov_b32_e32 v61, v151
	v_mov_b32_e32 v62, v151
	v_mov_b32_e32 v63, v151
	v_mov_b32_e32 v64, v151
	v_mov_b32_e32 v65, v151
	s_mov_b32 s22, 0xc1200000
	s_mov_b32 s34, 0xc1800000
	s_mov_b32 s36, 0xc1900000
	s_mov_b32 s38, 0xc1c00000
	s_mov_b32 s40, 0xc1d00000
	v_mov_b64_e32 v[34:35], v[50:51]
	s_mov_b32 s11, 0xc1100000
	s_mov_b32 s23, 0xc1300000
	s_mov_b32 s35, 0xc1880000
	s_mov_b32 s37, 0xc1980000
	s_mov_b32 s39, 0xc1c80000
	s_mov_b32 s41, 0xc1d80000
	s_mov_b32 s44, 0x41000000
	v_mov_b64_e32 v[36:37], v[52:53]
	v_mov_b64_e32 v[38:39], v[54:55]
	v_mov_b64_e32 v[40:41], v[56:57]
	v_mov_b64_e32 v[42:43], v[58:59]
	v_mov_b64_e32 v[44:45], v[60:61]
	v_mov_b64_e32 v[46:47], v[62:63]
	v_mov_b64_e32 v[48:49], v[64:65]
	v_mov_b32_e32 v180, v151
	v_mov_b32_e32 v66, v151
	v_mov_b32_e32 v67, v151
	v_mov_b32_e32 v68, v151
	v_mov_b32_e32 v69, v151
	v_mov_b32_e32 v70, v151
	v_mov_b32_e32 v71, v151
	v_mov_b32_e32 v72, v151
	v_mov_b32_e32 v73, v151
	v_mov_b32_e32 v74, v151
	v_mov_b32_e32 v75, v151
	v_mov_b32_e32 v76, v151
	v_mov_b32_e32 v77, v151
	v_mov_b32_e32 v78, v151
	v_mov_b32_e32 v79, v151
	v_mov_b32_e32 v80, v151
	v_mov_b32_e32 v81, v151
	s_waitcnt vmcnt(3)
; __device__ __forceinline__ unsigned cvtpk(float lo, float hi) { typedef __bf16 bf2 __attribute__((ext_vector_type(2))); f32x2 v = {lo, hi}; bf2 b = __builtin_convertvector(v, bf2); return __builtin_bit_cast(unsigned, b); }
; template <int DQK, int DV, bool BIAS> ...
;     ...
;     for (int ks = 0; ks < NKS; ++ks) qf[ks] = ks < 4 ? *(const bf16x8*)(Qw + (size_t)r32 * ldq + ks * 16 + hi * 8) : *(const bf16x8*)(Q2w + (size_t)r32 * ldq2 + (ks - 4) * 16 + hi * 8);
; #pragma unroll
;     for (int ks = 0; ks < 4; ++ks) qf[ks] = scale_frag(qf[ks], cs);
;     if constexpr (DQK == 96) {
;         const float* rp = ropetab + ((size_t)(qpos0 + r32) * 16) * 2;
; #pragma unroll
;         for (int ks = 4; ks < 6; ++ks) {
;             const f32x4 c0 = *(const f32x4*)(rp + ((ks - 4) * 8 + hi * 4) * 2), c1 = *(const f32x4*)(rp + ((ks - 4) * 8 + hi * 4 + 2) * 2);
;             const u32x4 w = __builtin_bit_cast(u32x4, qf[ks]); u32x4 ow;
;             { const float a = bflo(w.x) * cs, b = bfhi(w.x) * cs; ow.x = cvtpk(a * c0[0] - b * c0[1], a * c0[1] + b * c0[0]); }
;             { const float a = bflo(w.y) * cs, b = bfhi(w.y) * cs; ow.y = cvtpk(a * c0[2] - b * c0[3], a * c0[3] + b * c0[2]); }
;             { const float a = bflo(w.z) * cs, b = bfhi(w.z) * cs; ow.z = cvtpk(a * c1[0] - b * c1[1], a * c1[1] + b * c1[0]); }
;             { const float a = bflo(w.w) * cs, b = bfhi(w.w) * cs; ow.w = cvtpk(a * c1[2] - b * c1[3], a * c1[3] + b * c1[2]); }
;             qf[ks] = __builtin_bit_cast(bf16x8, ow);
;         }
;     }
; #pragma unroll
;     for (int d = 0; d < NDT; ++d)
; #pragma unroll
;         for (int r = 0; r < 16; ++r) o[d][r] = 0.f;
; #pragma unroll
;     for (int ks = 0; ks < NKS; ++ks) asm volatile("" : "+v"(qf[ks]));
;     float mhat = 0.f, l = 0.f; f32x16 negm;
; #pragma unroll
;     for (int r = 0; r < 16; ++r) negm[r] = 0.f;
;     constexpr int TPB = (DV == 64) ? 2 : 1, NG = SEQL / 64 / TPB;
;     u32x4 kreg[TPB], k2reg[TPB], vreg[TPB][NVL];
;     const bf16_t* kptr = Kg + (size_t)(tid >> 3) * ldk + (tid & 7) * 8;
;     const bf16_t* k2ptr = (DQK == 96) ? K2g + (size_t)(tid >> 2) * ldk2 + (tid & 3) * 8 : nullptr;
;     ...
;     u32x4 pw[4];
; #pragma unroll
;     for (int j = 0; j < TPB; ++j) { ATT_LOAD(j, j); ATT_STORE(j, j); }
; #pragma unroll
;     for (int j = 0; j < TPB; ++j) ATT_LOAD(TPB + j, j);
;     const float qp = (float)(qpos0 + r32);
	v_lshlrev_b32_e32 v18, 16, v2
	v_and_b32_e32 v19, 0xffff0000, v2
	v_lshlrev_b32_e32 v2, 16, v3
	v_and_b32_e32 v3, 0xffff0000, v3
	v_pk_mul_f32 v[2:3], v[2:3], s[6:7] op_sel_hi:[1,0]
	v_pk_mul_f32 v[18:19], v[18:19], s[6:7] op_sel_hi:[1,0]
	v_cvt_pk_bf16_f32 v115, v2, v3
	v_lshlrev_b32_e32 v2, 16, v4
	v_and_b32_e32 v3, 0xffff0000, v4
	v_pk_mul_f32 v[2:3], v[2:3], s[6:7] op_sel_hi:[1,0]
	v_cvt_pk_bf16_f32 v114, v18, v19
	v_cvt_pk_bf16_f32 v116, v2, v3
	v_lshlrev_b32_e32 v2, 16, v5
	v_and_b32_e32 v3, 0xffff0000, v5
	v_pk_mul_f32 v[2:3], v[2:3], s[6:7] op_sel_hi:[1,0]
	s_nop 0
	v_cvt_pk_bf16_f32 v117, v2, v3
	s_waitcnt vmcnt(2)
	v_lshlrev_b32_e32 v2, 16, v6
	v_and_b32_e32 v3, 0xffff0000, v6
	v_pk_mul_f32 v[2:3], v[2:3], s[6:7] op_sel_hi:[1,0]
	s_nop 0
	v_cvt_pk_bf16_f32 v118, v2, v3
	v_lshlrev_b32_e32 v2, 16, v7
	v_and_b32_e32 v3, 0xffff0000, v7
	v_pk_mul_f32 v[2:3], v[2:3], s[6:7] op_sel_hi:[1,0]
	s_nop 0
	v_cvt_pk_bf16_f32 v119, v2, v3
	v_lshlrev_b32_e32 v2, 16, v8
	v_and_b32_e32 v3, 0xffff0000, v8
	v_pk_mul_f32 v[2:3], v[2:3], s[6:7] op_sel_hi:[1,0]
	v_lshlrev_b32_e32 v8, 3, v22
	v_cvt_pk_bf16_f32 v120, v2, v3
	v_lshlrev_b32_e32 v2, 16, v9
	v_and_b32_e32 v3, 0xffff0000, v9
	v_pk_mul_f32 v[2:3], v[2:3], s[6:7] op_sel_hi:[1,0]
	v_and_b32_e32 v27, 24, v8
	v_cvt_pk_bf16_f32 v121, v2, v3
	s_waitcnt vmcnt(1)
	v_lshlrev_b32_e32 v2, 16, v10
	v_and_b32_e32 v3, 0xffff0000, v10
	v_pk_mul_f32 v[2:3], v[2:3], s[6:7] op_sel_hi:[1,0]
	v_add_u32_e32 v10, 0x200, v22
	v_cvt_pk_bf16_f32 v122, v2, v3
	v_lshlrev_b32_e32 v2, 16, v11
	v_and_b32_e32 v3, 0xffff0000, v11
	v_pk_mul_f32 v[2:3], v[2:3], s[6:7] op_sel_hi:[1,0]
	v_lshlrev_b32_e32 v8, 1, v27
	v_cvt_pk_bf16_f32 v123, v2, v3
	v_lshlrev_b32_e32 v2, 16, v12
	v_and_b32_e32 v3, 0xffff0000, v12
	v_pk_mul_f32 v[2:3], v[2:3], s[6:7] op_sel_hi:[1,0]
	v_mov_b32_e32 v9, v151
	v_cvt_pk_bf16_f32 v124, v2, v3
	v_lshlrev_b32_e32 v2, 16, v13
	v_and_b32_e32 v3, 0xffff0000, v13
	v_pk_mul_f32 v[2:3], v[2:3], s[6:7] op_sel_hi:[1,0]
	v_ashrrev_i32_e32 v10, 3, v10
	v_cvt_pk_bf16_f32 v125, v2, v3
	s_waitcnt vmcnt(0)
	v_lshlrev_b32_e32 v2, 16, v14
	v_and_b32_e32 v3, 0xffff0000, v14
	v_pk_mul_f32 v[2:3], v[2:3], s[6:7] op_sel_hi:[1,0]
	v_and_b32_e32 v14, 0x70, v26
	v_cvt_pk_bf16_f32 v126, v2, v3
	v_lshlrev_b32_e32 v2, 16, v15
	v_and_b32_e32 v3, 0xffff0000, v15
	v_pk_mul_f32 v[2:3], v[2:3], s[6:7] op_sel_hi:[1,0]
	v_mov_b32_e32 v15, v151
	v_cvt_pk_bf16_f32 v127, v2, v3
	v_lshlrev_b32_e32 v2, 16, v16
	v_and_b32_e32 v3, 0xffff0000, v16
	v_pk_mul_f32 v[2:3], v[2:3], s[6:7] op_sel_hi:[1,0]
	v_and_b32_e32 v10, 0xffffffe0, v10
	v_cvt_pk_bf16_f32 v128, v2, v3
	v_lshlrev_b32_e32 v2, 16, v17
	v_and_b32_e32 v3, 0xffff0000, v17
	v_pk_mul_f32 v[2:3], v[2:3], s[6:7] op_sel_hi:[1,0]
	v_ashrrev_i32_e32 v11, 31, v10
	v_cvt_pk_bf16_f32 v129, v2, v3
	v_mov_b64_e32 v[2:3], s[4:5]
	v_mad_i64_i32 v[2:3], s[6:7], v25, s8, v[2:3]
	v_lshl_add_u64 v[144:145], v[2:3], 0, v[14:15]
	v_subrev_u32_e32 v232, s4, v144
	s_sub_u32 s98, s4, s16
	s_subb_u32 s99, s5, s17
	v_bfe_u32 v15, v22, 2, 6
	v_mul_u32_u24_e32 v2, 0xca0, v15
	v_lshlrev_b32_e32 v2, 1, v2
	v_mov_b32_e32 v3, v151
	v_lshl_add_u64 v[6:7], s[4:5], 0, v[2:3]
	global_load_dwordx4 v[2:5], v[144:145], off offset:1152
	v_lshl_add_u64 v[16:17], v[6:7], 0, v[8:9]
	v_and_b32_e32 v6, 0xffffffe0, v25
	s_movk_i32 s6, 0x90
	v_ashrrev_i32_e32 v7, 31, v6
	v_mul_lo_u32 v25, v25, s6
	v_lshlrev_b64 v[18:19], 1, v[6:7]
	v_lshlrev_b64 v[20:21], 1, v[10:11]
	v_add_u32_e32 v25, 0, v25
	v_lshl_add_u64 v[6:7], v[16:17], 0, v[18:19]
	v_lshl_add_u64 v[10:11], v[16:17], 0, v[20:21]
	v_add_u32_e32 v174, v25, v14
	s_mov_b64 s[4:5], 0x65800
	global_load_dwordx4 v[6:9], v[6:7], off offset:2048
	v_add3_u32 v14, 0, v29, v30
	global_load_dwordx4 v[10:13], v[10:11], off offset:2048
	v_and_b32_e32 v25, 0xfffff000, v26
	v_add_u32_e32 v175, v14, v25
	s_mov_b32 s7, 0
	s_waitcnt vmcnt(2)
	ds_write_b128 v174, v[2:5]
	v_lshl_add_u64 v[2:3], v[16:17], 0, s[4:5]
	v_lshl_add_u64 v[4:5], v[2:3], 0, v[18:19]
	s_mov_b32 s4, 0x65000
	global_load_dwordx4 v[130:133], v[4:5], off
	v_lshl_add_u64 v[2:3], v[2:3], 0, v[20:21]
	v_add_co_u32_e32 v4, vcc, s4, v144
	s_add_u32 s4, s9, s49
	s_nop 0
	v_addc_co_u32_e32 v5, vcc, 0, v145, vcc
	global_load_dwordx4 v[134:137], v[2:3], off
	global_load_dwordx4 v[138:141], v[4:5], off offset:1152
	v_or_b32_e32 v2, s3, v23
	v_cvt_f32_i32_e32 v176, v2
	v_and_or_b32 v2, v28, 3, v177
	v_lshlrev_b32_e32 v3, 1, v22
	v_lshl_add_u32 v2, v2, 6, 0
	v_and_b32_e32 v3, 32, v3
	s_addc_u32 s5, 0, s48
	v_add3_u32 v178, v2, v3, v27
	v_mov_b64_e32 v[2:3], s[4:5]
	v_and_b32_e32 v4, 3, v22
	v_mad_u64_u32 v[2:3], s[4:5], v15, s8, v[2:3]
	v_lshlrev_b32_e32 v4, 4, v4
	v_mov_b32_e32 v5, v151
	v_lshl_add_u64 v[2:3], v[2:3], 0, v[4:5]
	s_waitcnt vmcnt(4)
	ds_write_b128 v175, v[6:9] offset:18432
	s_waitcnt vmcnt(3)
	ds_write_b128 v175, v[10:13] offset:26624
	v_mad_u32_u24 v6, v23, s6, 0
	v_lshl_add_u64 v[4:5], v[2:3], 0, v[20:21]
	v_lshl_add_u64 v[2:3], v[2:3], 0, v[18:19]
	v_mov_b32_e32 v231, v4
	v_lshl_add_u64 v[146:147], s[16:17], 0, v[4:5]
	v_mov_b32_e32 v230, v2
	v_lshl_add_u64 v[148:149], s[16:17], 0, v[2:3]
	s_mov_b32 s8, -2.0
	v_add_u32_e32 v179, v6, v150
	v_mov_b64_e32 v[18:19], v[50:51]
	v_mov_b64_e32 v[2:3], v[50:51]
	s_mov_b64 s[4:5], 0
	s_mov_b32 s6, 0xc2000000
	s_mov_b32 s9, 0xc0400000
	v_mov_b64_e32 v[20:21], v[52:53]
	v_mov_b64_e32 v[22:23], v[54:55]
	v_mov_b64_e32 v[24:25], v[56:57]
	v_mov_b64_e32 v[26:27], v[58:59]
	v_mov_b64_e32 v[28:29], v[60:61]
	v_mov_b64_e32 v[30:31], v[62:63]
	v_mov_b64_e32 v[32:33], v[64:65]
	v_mov_b64_e32 v[4:5], v[52:53]
	v_mov_b64_e32 v[6:7], v[54:55]
	v_mov_b64_e32 v[8:9], v[56:57]
	v_mov_b64_e32 v[10:11], v[58:59]
	v_mov_b64_e32 v[12:13], v[60:61]
	v_mov_b64_e32 v[14:15], v[62:63]
	v_mov_b64_e32 v[16:17], v[64:65]
	v_mov_b32_e32 v250, 0
	v_cvt_u32_f32_e32 v252, v176
	s_nop 0
	v_readfirstlane_b32 s96, v252
	s_nop 3
	s_lshr_b32 s96, s96, 6
	s_mov_b32 s97, 3
	s_branch .LBB0_588

; #define LAS __attribute__((address_space(3)))
; template <int DQK, int DV, bool BIAS> ...
;     ...
;     for (int g = 0; g < NG; ++g) {
;         const int pair = g & 1;
;         __syncthreads();
;         if (g + 1 < NG) {
; #pragma unroll
;             for (int j = 0; j < TPB; ++j) ATT_STORE((pair ^ 1) * TPB + j, j);
;             if (g + 2 < NG) {
; #pragma unroll
;                 for (int j = 0; j < TPB; ++j) ATT_LOAD((g + 2) * TPB + j, j);
;             }
;         }
; #pragma unroll
;       for (int sub = 0; sub < TPB; ++sub) {
;         const int t = g * TPB + sub, buf = pair * TPB + sub, vcur = buf;
;         f32x16 p0, p1;
;         const LAS unsigned char* kb = lds + buf * KBUF + r32 * KP + hi * 16;
; #pragma unroll
;         for (int ks = 0; ks < NKS; ++ks) {
;             const bf16x8 k0 = *(const LAS bf16x8*)(kb + ks * 32), k1 = *(const LAS bf16x8*)(kb + 32 * KP + ks * 32);
;             if (ks == 0) { p0 = __builtin_amdgcn_mfma_f32_32x32x16_bf16(k0, qf[0], negm, 0, 0, 0); p1 = __builtin_amdgcn_mfma_f32_32x32x16_bf16(k1, qf[0], negm, 0, 0, 0); }
;             else { p0 = __builtin_amdgcn_mfma_f32_32x32x16_bf16(k0, qf[ks], p0, 0, 0, 0); p1 = __builtin_amdgcn_mfma_f32_32x32x16_bf16(k1, qf[ks], p1, 0, 0, 0); }
;         }
;         if (BIAS) {
;             asm volatile("s_nop 15\n\ts_nop 7" : "+v"(p0), "+v"(p1));
;             const float d0 = qp - (float)(t * 64 + 4 * hi);
; #pragma unroll
;             for (int r = 0; r < 16; ++r) { const float dk = d0 - (float)((r & 3) + 8 * (r >> 2)); p0[r] = p0[r] - sl2 * fabsf(dk); p1[r] = p1[r] - sl2 * fabsf(dk - 32.f); }
;         } else {
;             asm volatile("s_nop 15\n\ts_nop 7" : "+v"(p0), "+v"(p1));
.LBB0_590:
	s_mov_b32 s100, s7
	s_cmp_lt_u32 s100, s96
	s_cselect_b32 s101, 1, 2
	s_cmp_eq_u32 s100, s96
	s_cselect_b32 s101, 0, s101
	s_cmp_eq_u32 s101, s97
	s_cbranch_scc1 .Lcb3_ok
	s_mov_b32 s97, s101
	s_cmp_eq_u32 s101, 1
	s_cselect_b32 s100, 0x3f800000, 0xbf800000
	s_cmp_eq_u32 s101, 0
	s_cselect_b32 s100, 0, s100
	v_mul_f32_e32 v251, s100, v142
	v_fmamk_f32 v66, v251, 0x00000000, v250
	v_fmamk_f32 v67, v251, 0x3f800000, v250
	v_fmamk_f32 v68, v251, 0x40000000, v250
	v_fmamk_f32 v69, v251, 0x40400000, v250
	v_fmamk_f32 v70, v251, 0x41000000, v250
	v_fmamk_f32 v71, v251, 0x41100000, v250
	v_fmamk_f32 v72, v251, 0x41200000, v250
	v_fmamk_f32 v73, v251, 0x41300000, v250
	v_fmamk_f32 v74, v251, 0x41800000, v250
	v_fmamk_f32 v75, v251, 0x41880000, v250
	v_fmamk_f32 v76, v251, 0x41900000, v250
	v_fmamk_f32 v77, v251, 0x41980000, v250
	v_fmamk_f32 v78, v251, 0x41c00000, v250
	v_fmamk_f32 v79, v251, 0x41c80000, v250
	v_fmamk_f32 v80, v251, 0x41d00000, v250
	v_fmamk_f32 v81, v251, 0x41d80000, v250
	v_fmamk_f32 v234, v251, 0x42000000, v250
	v_fmamk_f32 v235, v251, 0x42040000, v250
	v_fmamk_f32 v236, v251, 0x42080000, v250
	v_fmamk_f32 v237, v251, 0x420c0000, v250
	v_fmamk_f32 v238, v251, 0x42200000, v250
	v_fmamk_f32 v239, v251, 0x42240000, v250
	v_fmamk_f32 v240, v251, 0x42280000, v250
	v_fmamk_f32 v241, v251, 0x422c0000, v250
	v_fmamk_f32 v242, v251, 0x42400000, v250
	v_fmamk_f32 v243, v251, 0x42440000, v250
	v_fmamk_f32 v244, v251, 0x42480000, v250
	v_fmamk_f32 v245, v251, 0x424c0000, v250
	v_fmamk_f32 v246, v251, 0x42600000, v250
	v_fmamk_f32 v247, v251, 0x42640000, v250
	v_fmamk_f32 v248, v251, 0x42680000, v250
	v_fmamk_f32 v249, v251, 0x426c0000, v250
	s_nop 1
.Lcb3_ok:
	ds_read_b128 v[82:85], v179
	ds_read_b128 v[152:155], v179 offset:32
	ds_read_b128 v[156:159], v179 offset:4608
	ds_read_b128 v[160:163], v179 offset:4640
	v_cvt_f32_u32_e32 v150, v177
	s_waitcnt lgkmcnt(3)
	v_mfma_f32_32x32x16_bf16 v[98:113], v[82:85], v[114:117], v[66:81]
	v_sub_f32_e32 v182, v176, v150
	v_add_f32_e32 v183, -1.0, v182
	s_waitcnt lgkmcnt(1)
	v_mfma_f32_32x32x16_bf16 v[82:97], v[156:159], v[114:117], v[234:249]
	v_mfma_f32_32x32x16_bf16 v[98:113], v[152:155], v[118:121], v[98:113]
	ds_read_b128 v[152:155], v179 offset:64
	ds_read_b128 v[156:159], v179 offset:96
	s_waitcnt lgkmcnt(2)
	v_mfma_f32_32x32x16_bf16 v[82:97], v[160:163], v[118:121], v[82:97]
	s_waitcnt lgkmcnt(1)
	v_mfma_f32_32x32x16_bf16 v[98:113], v[152:155], v[122:125], v[98:113]
	ds_read_b128 v[152:155], v179 offset:4672
	ds_read_b128 v[160:163], v179 offset:4704
	s_waitcnt lgkmcnt(1)
	v_mfma_f32_32x32x16_bf16 v[82:97], v[152:155], v[122:125], v[82:97]
	v_mfma_f32_32x32x16_bf16 v[98:113], v[156:159], v[126:129], v[98:113]
	s_waitcnt lgkmcnt(0)
	v_mfma_f32_32x32x16_bf16 v[82:97], v[160:163], v[126:129], v[82:97]
	s_nop 15
	s_nop 7
	s_nop 9
	s_cmp_eq_u32 s7, s96
	s_cbranch_scc1 .Lcb3_d
	v_mul_f32_e64 v252, -v251, v182
	v_add_f32_e32 v156, v252, v98
	v_add_f32_e32 v157, v252, v99
	v_add_f32_e32 v99, v252, v83
	v_add_f32_e32 v98, v252, v82
	v_add_f32_e32 v161, v252, v101
	v_add_f32_e32 v160, v252, v100
	v_add_f32_e32 v153, v252, v85
	v_add_f32_e32 v152, v252, v84
	v_add_f32_e32 v165, v252, v103
	v_add_f32_e32 v164, v252, v102
	v_add_f32_e32 v103, v252, v87
	v_add_f32_e32 v102, v252, v86
	v_add_f32_e32 v167, v252, v105
	v_add_f32_e32 v166, v252, v104
	v_add_f32_e32 v155, v252, v89
	v_add_f32_e32 v154, v252, v88
	v_add_f32_e32 v159, v252, v107
	v_add_f32_e32 v158, v252, v106
	v_add_f32_e32 v101, v252, v91
	v_add_f32_e32 v100, v252, v90
	v_add_f32_e32 v163, v252, v109
	v_add_f32_e32 v162, v252, v108
	v_add_f32_e32 v105, v252, v93
	v_add_f32_e32 v104, v252, v92
	v_add_f32_e32 v111, v252, v111
	v_add_f32_e32 v110, v252, v110
	v_add_f32_e32 v107, v252, v95
	v_add_f32_e32 v106, v252, v94
	v_add_f32_e32 v113, v252, v113
	v_add_f32_e32 v112, v252, v112
	v_add_f32_e32 v109, v252, v97
	v_add_f32_e32 v108, v252, v96
	s_branch .Lcb3_j
.Lcb3_d:
	v_fma_f32 v156, -v142, |v182|, v98
	v_fma_f32 v157, -v143, |v183|, v99
	v_pk_add_f32 v[98:99], v[182:183], s[6:7] op_sel_hi:[1,0]
	s_nop 0
	v_fma_f32 v99, -v143, |v99|, v83
	v_fma_f32 v98, -v142, |v98|, v82
	v_pk_add_f32 v[82:83], v[182:183], s[8:9] op_sel_hi:[0,1]
	v_fma_f32 v161, -v143, |v83|, v101
	v_fma_f32 v160, -v142, |v82|, v100
	v_pk_add_f32 v[82:83], v[82:83], s[6:7] op_sel_hi:[1,0]
	v_fma_f32 v153, -v143, |v83|, v85
	v_fma_f32 v152, -v142, |v82|, v84
	v_pk_add_f32 v[82:83], v[182:183], s[10:11] op_sel_hi:[0,1]
	v_fma_f32 v165, -v143, |v83|, v103
	v_fma_f32 v164, -v142, |v82|, v102
	v_pk_add_f32 v[82:83], v[82:83], s[6:7] op_sel_hi:[1,0]
	v_fma_f32 v103, -v143, |v83|, v87
	v_fma_f32 v102, -v142, |v82|, v86
	v_pk_add_f32 v[82:83], v[182:183], s[22:23] op_sel_hi:[0,1]
	v_fma_f32 v167, -v143, |v83|, v105
	v_fma_f32 v166, -v142, |v82|, v104
	v_pk_add_f32 v[82:83], v[82:83], s[6:7] op_sel_hi:[1,0]
	v_fma_f32 v155, -v143, |v83|, v89
	v_fma_f32 v154, -v142, |v82|, v88
	v_pk_add_f32 v[82:83], v[182:183], s[34:35] op_sel_hi:[0,1]
	v_fma_f32 v159, -v143, |v83|, v107
	v_fma_f32 v158, -v142, |v82|, v106
	v_pk_add_f32 v[82:83], v[82:83], s[6:7] op_sel_hi:[1,0]
	v_fma_f32 v101, -v143, |v83|, v91
	v_fma_f32 v100, -v142, |v82|, v90
	v_pk_add_f32 v[82:83], v[182:183], s[36:37] op_sel_hi:[0,1]
	v_fma_f32 v163, -v143, |v83|, v109
	v_fma_f32 v162, -v142, |v82|, v108
	v_pk_add_f32 v[82:83], v[82:83], s[6:7] op_sel_hi:[1,0]
	v_fma_f32 v105, -v143, |v83|, v93
	v_fma_f32 v104, -v142, |v82|, v92
	v_pk_add_f32 v[82:83], v[182:183], s[38:39] op_sel_hi:[0,1]
	v_fma_f32 v111, -v143, |v83|, v111
	v_fma_f32 v110, -v142, |v82|, v110
	v_pk_add_f32 v[82:83], v[82:83], s[6:7] op_sel_hi:[1,0]
	v_fma_f32 v107, -v143, |v83|, v95
	v_fma_f32 v106, -v142, |v82|, v94
	v_pk_add_f32 v[82:83], v[182:183], s[40:41] op_sel_hi:[0,1]
	v_fma_f32 v113, -v143, |v83|, v113
	v_fma_f32 v112, -v142, |v82|, v112
	v_pk_add_f32 v[82:83], v[82:83], s[6:7] op_sel_hi:[1,0]
	v_fma_f32 v109, -v143, |v83|, v97
	v_fma_f32 v108, -v142, |v82|, v96
; __device__ __forceinline__ float max3f(float a, float b, float c) { float r; asm("v_max3_f32 %0, %1, %2, %3" : "=v"(r) : "v"(a), "v"(b), "v"(c)); return r; }
; template <int DQK, int DV, bool BIAS> ...
;     ...
;         float mxa = max3f(p0[0], p0[1], p1[0]), mxb = max3f(p0[2], p0[3], p1[1]); mxa = max3f(mxa, p1[2], p1[3]);
; #pragma unroll
;         for (int r = 4; r < 16; r += 4) { mxa = max3f(mxa, p0[r], p0[r + 1]); mxb = max3f(mxb, p0[r + 2], p0[r + 3]); mxa = max3f(mxa, p1[r], p1[r + 1]); mxb = max3f(mxb, p1[r + 2], p1[r + 3]); }
;         float mx = fmaxf(mxa, mxb);
;         if (__any(mx > 8.f)) {
;             mx = fmaxf(mx, __shfl_xor(mx, 32));
;             const float dl = fmaxf(mx, 0.f); mhat += dl;
;             const float f = __builtin_amdgcn_exp2f(-dl);
; #pragma unroll
;             for (int r = 0; r < 16; ++r) { p0[r] -= dl; p1[r] -= dl; negm[r] = -mhat; }
;             l *= f;
; #pragma unroll
;             for (int d = 0; d < NDT; ++d)
; #pragma unroll
;                 for (int r = 0; r < 16; ++r) o[d][r] *= f;
;         }
.Lcb3_j:
	v_max3_f32 v82, v156, v157, v98
	v_max3_f32 v83, v160, v161, v99
	v_max3_f32 v82, v82, v152, v153
	v_max3_f32 v83, v83, v166, v167
	v_max3_f32 v82, v82, v164, v165
	v_max3_f32 v83, v83, v154, v155
	v_max3_f32 v82, v82, v102, v103
	v_max3_f32 v83, v83, v162, v163
	v_max3_f32 v82, v82, v158, v159
	v_max3_f32 v83, v83, v104, v105
	v_max3_f32 v82, v82, v100, v101
	v_max3_f32 v83, v83, v112, v113
	v_max3_f32 v82, v82, v110, v111
	v_max3_f32 v83, v83, v108, v109
	v_max3_f32 v82, v82, v106, v107
	v_max_f32_e32 v82, v82, v83
	v_cmp_gt_f32_e32 vcc, 0xc3400000, v82
	s_cmp_eq_u64 vcc, exec
	s_cbranch_scc1 .Lsk1_p4a2
	v_cmp_lt_f32_e32 vcc, s44, v82
	s_cbranch_vccz .LBB0_592
	ds_bpermute_b32 v66, v168, v82
	s_waitcnt lgkmcnt(0)
	v_max3_f32 v67, v82, v66, 0
	v_exp_f32_e64 v66, -v67
	v_add_f32_e32 v180, v180, v67
	v_xor_b32_e32 v82, 0x80000000, v180
	v_sub_f32_e32 v98, v98, v67
	v_sub_f32_e32 v99, v99, v67
	v_sub_f32_e32 v152, v152, v67
	v_sub_f32_e32 v153, v153, v67
	v_sub_f32_e32 v102, v102, v67
	v_sub_f32_e32 v103, v103, v67
	v_sub_f32_e32 v154, v154, v67
	v_sub_f32_e32 v155, v155, v67
	v_sub_f32_e32 v100, v100, v67
	v_sub_f32_e32 v101, v101, v67
	v_sub_f32_e32 v104, v104, v67
	v_sub_f32_e32 v105, v105, v67
	v_sub_f32_e32 v106, v106, v67
	v_sub_f32_e32 v107, v107, v67
	v_sub_f32_e32 v108, v108, v67
	v_sub_f32_e32 v109, v109, v67
	v_pk_mul_f32 v[16:17], v[16:17], v[66:67] op_sel_hi:[1,0]
	v_pk_mul_f32 v[14:15], v[14:15], v[66:67] op_sel_hi:[1,0]
	v_pk_mul_f32 v[12:13], v[12:13], v[66:67] op_sel_hi:[1,0]
	v_pk_mul_f32 v[10:11], v[10:11], v[66:67] op_sel_hi:[1,0]
	v_pk_mul_f32 v[8:9], v[8:9], v[66:67] op_sel_hi:[1,0]
	v_pk_mul_f32 v[6:7], v[6:7], v[66:67] op_sel_hi:[1,0]
	v_pk_mul_f32 v[4:5], v[4:5], v[66:67] op_sel_hi:[1,0]
	v_pk_mul_f32 v[2:3], v[2:3], v[66:67] op_sel_hi:[1,0]
	v_pk_mul_f32 v[32:33], v[32:33], v[66:67] op_sel_hi:[1,0]
	v_pk_mul_f32 v[30:31], v[30:31], v[66:67] op_sel_hi:[1,0]
	v_pk_mul_f32 v[28:29], v[28:29], v[66:67] op_sel_hi:[1,0]
	v_pk_mul_f32 v[26:27], v[26:27], v[66:67] op_sel_hi:[1,0]
	v_pk_mul_f32 v[24:25], v[24:25], v[66:67] op_sel_hi:[1,0]
	v_pk_mul_f32 v[22:23], v[22:23], v[66:67] op_sel_hi:[1,0]
	v_pk_mul_f32 v[20:21], v[20:21], v[66:67] op_sel_hi:[1,0]
	v_pk_mul_f32 v[18:19], v[18:19], v[66:67] op_sel_hi:[1,0]
	v_pk_mul_f32 v[48:49], v[48:49], v[66:67] op_sel_hi:[1,0]
	v_pk_mul_f32 v[46:47], v[46:47], v[66:67] op_sel_hi:[1,0]
	v_pk_mul_f32 v[44:45], v[44:45], v[66:67] op_sel_hi:[1,0]
	v_pk_mul_f32 v[42:43], v[42:43], v[66:67] op_sel_hi:[1,0]
	v_pk_mul_f32 v[40:41], v[40:41], v[66:67] op_sel_hi:[1,0]
	v_pk_mul_f32 v[38:39], v[38:39], v[66:67] op_sel_hi:[1,0]
	v_pk_mul_f32 v[36:37], v[36:37], v[66:67] op_sel_hi:[1,0]
	v_pk_mul_f32 v[34:35], v[34:35], v[66:67] op_sel_hi:[1,0]
	v_pk_mul_f32 v[64:65], v[64:65], v[66:67] op_sel_hi:[1,0]
	v_pk_mul_f32 v[62:63], v[62:63], v[66:67] op_sel_hi:[1,0]
	v_pk_mul_f32 v[60:61], v[60:61], v[66:67] op_sel_hi:[1,0]
	v_pk_mul_f32 v[58:59], v[58:59], v[66:67] op_sel_hi:[1,0]
	v_pk_mul_f32 v[56:57], v[56:57], v[66:67] op_sel_hi:[1,0]
	v_pk_mul_f32 v[54:55], v[54:55], v[66:67] op_sel_hi:[1,0]
	v_pk_mul_f32 v[52:53], v[52:53], v[66:67] op_sel_hi:[1,0]
	v_pk_mul_f32 v[50:51], v[50:51], v[66:67] op_sel_hi:[1,0]
	v_sub_f32_e32 v156, v156, v67
	v_sub_f32_e32 v157, v157, v67
	v_sub_f32_e32 v160, v160, v67
	v_sub_f32_e32 v161, v161, v67
	v_sub_f32_e32 v164, v164, v67
	v_sub_f32_e32 v165, v165, v67
	v_sub_f32_e32 v166, v166, v67
	v_sub_f32_e32 v167, v167, v67
	v_sub_f32_e32 v158, v158, v67
	v_sub_f32_e32 v159, v159, v67
	v_sub_f32_e32 v162, v162, v67
	v_sub_f32_e32 v163, v163, v67
	v_sub_f32_e32 v110, v110, v67
	v_sub_f32_e32 v111, v111, v67
	v_sub_f32_e32 v112, v112, v67
	v_sub_f32_e32 v113, v113, v67
	v_mul_f32_e32 v151, v151, v66
	v_mov_b32_e32 v250, v82
	v_fmamk_f32 v66, v251, 0x00000000, v250
	v_fmamk_f32 v67, v251, 0x3f800000, v250
	v_fmamk_f32 v68, v251, 0x40000000, v250
	v_fmamk_f32 v69, v251, 0x40400000, v250
	v_fmamk_f32 v70, v251, 0x41000000, v250
	v_fmamk_f32 v71, v251, 0x41100000, v250
	v_fmamk_f32 v72, v251, 0x41200000, v250
	v_fmamk_f32 v73, v251, 0x41300000, v250
	v_fmamk_f32 v74, v251, 0x41800000, v250
	v_fmamk_f32 v75, v251, 0x41880000, v250
	v_fmamk_f32 v76, v251, 0x41900000, v250
	v_fmamk_f32 v77, v251, 0x41980000, v250
	v_fmamk_f32 v78, v251, 0x41c00000, v250
	v_fmamk_f32 v79, v251, 0x41c80000, v250
	v_fmamk_f32 v80, v251, 0x41d00000, v250
	v_fmamk_f32 v81, v251, 0x41d80000, v250
	v_fmamk_f32 v234, v251, 0x42000000, v250
	v_fmamk_f32 v235, v251, 0x42040000, v250
	v_fmamk_f32 v236, v251, 0x42080000, v250
	v_fmamk_f32 v237, v251, 0x420c0000, v250
	v_fmamk_f32 v238, v251, 0x42200000, v250
	v_fmamk_f32 v239, v251, 0x42240000, v250
	v_fmamk_f32 v240, v251, 0x42280000, v250
	v_fmamk_f32 v241, v251, 0x422c0000, v250
	v_fmamk_f32 v242, v251, 0x42400000, v250
	v_fmamk_f32 v243, v251, 0x42440000, v250
	v_fmamk_f32 v244, v251, 0x42480000, v250
	v_fmamk_f32 v245, v251, 0x424c0000, v250
	v_fmamk_f32 v246, v251, 0x42600000, v250
	v_fmamk_f32 v247, v251, 0x42640000, v250
	v_fmamk_f32 v248, v251, 0x42680000, v250
	v_fmamk_f32 v249, v251, 0x426c0000, v250
	s_branch .LBB0_593

; #define LAS __attribute__((address_space(3)))
; template <int DQK, int DV, bool BIAS> ...
;     ...
;     for (int g = 0; g < NG; ++g) {
;         const int pair = g & 1;
;         __syncthreads();
;         if (g + 1 < NG) {
; #pragma unroll
;             for (int j = 0; j < TPB; ++j) ATT_STORE((pair ^ 1) * TPB + j, j);
;             if (g + 2 < NG) {
; #pragma unroll
;                 for (int j = 0; j < TPB; ++j) ATT_LOAD((g + 2) * TPB + j, j);
;             }
;         }
; #pragma unroll
;       for (int sub = 0; sub < TPB; ++sub) {
;         const int t = g * TPB + sub, buf = pair * TPB + sub, vcur = buf;
;         f32x16 p0, p1;
;         const LAS unsigned char* kb = lds + buf * KBUF + r32 * KP + hi * 16;
; #pragma unroll
;         for (int ks = 0; ks < NKS; ++ks) {
;             const bf16x8 k0 = *(const LAS bf16x8*)(kb + ks * 32), k1 = *(const LAS bf16x8*)(kb + 32 * KP + ks * 32);
;             if (ks == 0) { p0 = __builtin_amdgcn_mfma_f32_32x32x16_bf16(k0, qf[0], negm, 0, 0, 0); p1 = __builtin_amdgcn_mfma_f32_32x32x16_bf16(k1, qf[0], negm, 0, 0, 0); }
;             else { p0 = __builtin_amdgcn_mfma_f32_32x32x16_bf16(k0, qf[ks], p0, 0, 0, 0); p1 = __builtin_amdgcn_mfma_f32_32x32x16_bf16(k1, qf[ks], p1, 0, 0, 0); }
;         }
;         if (BIAS) {
;             asm volatile("s_nop 15\n\ts_nop 7" : "+v"(p0), "+v"(p1));
;             const float d0 = qp - (float)(t * 64 + 4 * hi);
; #pragma unroll
;             for (int r = 0; r < 16; ++r) { const float dk = d0 - (float)((r & 3) + 8 * (r >> 2)); p0[r] = p0[r] - sl2 * fabsf(dk); p1[r] = p1[r] - sl2 * fabsf(dk - 32.f); }
;         } else {
;             asm volatile("s_nop 15\n\ts_nop 7" : "+v"(p0), "+v"(p1));
;     ...
;             float ls = 0.f;
; #pragma unroll
;             for (int hs = 0; hs < 4; ++hs) {
;                 float e[8];
; #pragma unroll
;                 for (int j = 0; j < 8; ++j) { e[j] = __builtin_amdgcn_exp2f(hs < 2 ? p0[8 * (hs & 1) + j] : p1[8 * (hs & 1) + j]); ls += e[j]; }
;                 pw[hs].x = cvtpk(e[0], e[1]); pw[hs].y = cvtpk(e[2], e[3]); pw[hs].z = cvtpk(e[4], e[5]); pw[hs].w = cvtpk(e[6], e[7]);
;                 const bf16x8 pbv = __builtin_bit_cast(bf16x8, pw[hs]);
; #pragma unroll
;                 for (int d = 0; d < NDT; ++d) { const LAS unsigned char* vp = vbase + d * 4096 + hs * 1024;
.LBB0_596:
	s_add_i32 s100, s7, 1
	s_cmp_lt_u32 s100, s96
	s_cselect_b32 s101, 1, 2
	s_cmp_eq_u32 s100, s96
	s_cselect_b32 s101, 0, s101
	s_cmp_eq_u32 s101, s97
	s_cbranch_scc1 .Lcb4_ok
	s_mov_b32 s97, s101
	s_cmp_eq_u32 s101, 1
	s_cselect_b32 s100, 0x3f800000, 0xbf800000
	s_cmp_eq_u32 s101, 0
	s_cselect_b32 s100, 0, s100
	v_mul_f32_e32 v251, s100, v142
	v_fmamk_f32 v66, v251, 0x00000000, v250
	v_fmamk_f32 v67, v251, 0x3f800000, v250
	v_fmamk_f32 v68, v251, 0x40000000, v250
	v_fmamk_f32 v69, v251, 0x40400000, v250
	v_fmamk_f32 v70, v251, 0x41000000, v250
	v_fmamk_f32 v71, v251, 0x41100000, v250
	v_fmamk_f32 v72, v251, 0x41200000, v250
	v_fmamk_f32 v73, v251, 0x41300000, v250
	v_fmamk_f32 v74, v251, 0x41800000, v250
	v_fmamk_f32 v75, v251, 0x41880000, v250
	v_fmamk_f32 v76, v251, 0x41900000, v250
	v_fmamk_f32 v77, v251, 0x41980000, v250
	v_fmamk_f32 v78, v251, 0x41c00000, v250
	v_fmamk_f32 v79, v251, 0x41c80000, v250
	v_fmamk_f32 v80, v251, 0x41d00000, v250
	v_fmamk_f32 v81, v251, 0x41d80000, v250
	v_fmamk_f32 v234, v251, 0x42000000, v250
	v_fmamk_f32 v235, v251, 0x42040000, v250
	v_fmamk_f32 v236, v251, 0x42080000, v250
	v_fmamk_f32 v237, v251, 0x420c0000, v250
	v_fmamk_f32 v238, v251, 0x42200000, v250
	v_fmamk_f32 v239, v251, 0x42240000, v250
	v_fmamk_f32 v240, v251, 0x42280000, v250
	v_fmamk_f32 v241, v251, 0x422c0000, v250
	v_fmamk_f32 v242, v251, 0x42400000, v250
	v_fmamk_f32 v243, v251, 0x42440000, v250
	v_fmamk_f32 v244, v251, 0x42480000, v250
	v_fmamk_f32 v245, v251, 0x424c0000, v250
	v_fmamk_f32 v246, v251, 0x42600000, v250
	v_fmamk_f32 v247, v251, 0x42640000, v250
	v_fmamk_f32 v248, v251, 0x42680000, v250
	v_fmamk_f32 v249, v251, 0x426c0000, v250
	s_nop 1
.Lcb4_ok:
	ds_read_b128 v[196:199], v179 offset:9216
	ds_read_b128 v[200:203], v179 offset:9248
	v_add_f32_e32 v156, v157, v156
	v_add_f32_e32 v156, v160, v156
	s_waitcnt lgkmcnt(1)
	v_mfma_f32_32x32x16_bf16 v[98:113], v[196:199], v[114:117], v[66:81]
	ds_read_b128 v[196:199], v179 offset:13824
	ds_read_b128 v[204:207], v179 offset:13856
	v_add_f32_e32 v156, v161, v156
	v_add_f32_e32 v156, v164, v156
	v_add_f32_e32 v150, v150, v156
	v_add_f32_e32 v150, v165, v150
	v_add_f32_e32 v150, v166, v150
	v_add_f32_e32 v150, v167, v150
	s_waitcnt lgkmcnt(1)
	v_mfma_f32_32x32x16_bf16 v[82:97], v[196:199], v[114:117], v[234:249]
	v_add_f32_e32 v150, v181, v150
	v_add_f32_e32 v150, v182, v150
	v_add_f32_e32 v150, v158, v150
	v_add_f32_e32 v150, v159, v150
	ds_read_b128 v[164:167], v179 offset:9280
	v_add_f32_e32 v150, v162, v150
	v_add_f32_e32 v150, v163, v150
	v_mfma_f32_32x32x16_bf16 v[98:113], v[200:203], v[118:121], v[98:113]
	v_add_f32_e32 v150, v183, v150
	v_add_f32_e32 v150, v184, v150
	v_add_f32_e32 v150, v185, v150
	v_add_f32_e32 v150, v152, v150
	ds_read_b128 v[156:159], v179 offset:13888
	ds_read_b128 v[160:163], v179 offset:9312
	v_add_f32_e32 v150, v153, v150
	v_add_f32_e32 v150, v186, v150
	s_waitcnt lgkmcnt(3)
	v_mfma_f32_32x32x16_bf16 v[82:97], v[204:207], v[118:121], v[82:97]
	v_add_f32_e32 v150, v187, v150
	v_add_f32_e32 v150, v154, v150
	v_add_f32_e32 v150, v155, v150
	v_add_f32_e32 v150, v188, v150
	v_add_f32_e32 v150, v189, v150
	v_add_u32_e32 v152, 64, v177
	v_add_f32_e32 v150, v190, v150
	s_waitcnt lgkmcnt(2)
	v_mfma_f32_32x32x16_bf16 v[98:113], v[164:167], v[122:125], v[98:113]
	ds_read_b128 v[164:167], v179 offset:13920
	v_cvt_f32_u32_e32 v152, v152
	v_add_f32_e32 v150, v191, v150
	v_add_f32_e32 v150, v192, v150
	v_add_f32_e32 v150, v195, v150
	v_add_f32_e32 v150, v193, v150
	v_add_f32_e32 v150, v194, v150
	s_waitcnt lgkmcnt(2)
	v_mfma_f32_32x32x16_bf16 v[82:97], v[156:159], v[122:125], v[82:97]
	v_add_f32_e32 v158, v151, v150
	s_waitcnt lgkmcnt(1)
	v_mfma_f32_32x32x16_bf16 v[98:113], v[160:163], v[126:129], v[98:113]
	v_sub_f32_e32 v160, v176, v152
	v_add_f32_e32 v161, -1.0, v160
	s_waitcnt lgkmcnt(0)
	v_mfma_f32_32x32x16_bf16 v[82:97], v[164:167], v[126:129], v[82:97]
	s_nop 15
	s_nop 7
	s_nop 5
	s_add_i32 s100, s7, 1
	s_cmp_eq_u32 s100, s96
	s_cbranch_scc1 .Lcb4_d
	v_mul_f32_e64 v252, -v251, v160
	v_add_f32_e32 v150, v252, v98
	v_add_f32_e32 v151, v252, v99
	v_add_f32_e32 v83, v252, v83
	v_add_f32_e32 v82, v252, v82
	v_add_f32_e32 v153, v252, v101
	v_add_f32_e32 v152, v252, v100
	v_add_f32_e32 v99, v252, v85
	v_add_f32_e32 v98, v252, v84
	v_add_f32_e32 v155, v252, v103
	v_add_f32_e32 v154, v252, v102
	v_add_f32_e32 v101, v252, v87
	v_add_f32_e32 v100, v252, v86
	v_add_f32_e32 v157, v252, v105
	v_add_f32_e32 v156, v252, v104
	v_add_f32_e32 v103, v252, v89
	v_add_f32_e32 v102, v252, v88
	v_add_f32_e32 v105, v252, v107
	v_add_f32_e32 v104, v252, v106
	v_add_f32_e32 v107, v252, v109
	v_add_f32_e32 v106, v252, v108
	v_add_f32_e32 v85, v252, v91
	v_add_f32_e32 v84, v252, v90
	v_add_f32_e32 v87, v252, v93
	v_add_f32_e32 v86, v252, v92
	v_add_f32_e32 v93, v252, v111
	v_add_f32_e32 v92, v252, v110
	v_add_f32_e32 v89, v252, v95
	v_add_f32_e32 v88, v252, v94
	v_add_f32_e32 v95, v252, v113
	v_add_f32_e32 v94, v252, v112
	v_add_f32_e32 v91, v252, v97
	v_add_f32_e32 v90, v252, v96
	s_branch .Lcb4_j
; template <int DQK, int DV, bool BIAS> ...
;     ...
;         if (BIAS) {
;             asm volatile("s_nop 15\n\ts_nop 7" : "+v"(p0), "+v"(p1));
;             const float d0 = qp - (float)(t * 64 + 4 * hi);
; #pragma unroll
;             for (int r = 0; r < 16; ++r) { const float dk = d0 - (float)((r & 3) + 8 * (r >> 2)); p0[r] = p0[r] - sl2 * fabsf(dk); p1[r] = p1[r] - sl2 * fabsf(dk - 32.f); }
.Lcb4_d:
	v_fma_f32 v150, -v142, |v160|, v98
	v_fma_f32 v151, -v143, |v161|, v99
	v_pk_add_f32 v[98:99], v[160:161], s[6:7] op_sel_hi:[1,0]
	s_nop 0
	v_fma_f32 v83, -v143, |v99|, v83
	v_fma_f32 v82, -v142, |v98|, v82
	s_nop 0
	v_pk_add_f32 v[98:99], v[160:161], s[8:9] op_sel_hi:[0,1]
	v_fma_f32 v153, -v143, |v99|, v101
	v_fma_f32 v152, -v142, |v98|, v100
	v_pk_add_f32 v[98:99], v[98:99], s[6:7] op_sel_hi:[1,0]
	v_fma_f32 v99, -v143, |v99|, v85
	v_fma_f32 v98, -v142, |v98|, v84
	v_pk_add_f32 v[84:85], v[160:161], s[10:11] op_sel_hi:[0,1]
	v_fma_f32 v155, -v143, |v85|, v103
	v_fma_f32 v154, -v142, |v84|, v102
	v_pk_add_f32 v[84:85], v[84:85], s[6:7] op_sel_hi:[1,0]
	v_fma_f32 v101, -v143, |v85|, v87
	v_fma_f32 v100, -v142, |v84|, v86
	v_pk_add_f32 v[84:85], v[160:161], s[22:23] op_sel_hi:[0,1]
	v_fma_f32 v157, -v143, |v85|, v105
	v_fma_f32 v156, -v142, |v84|, v104
	v_pk_add_f32 v[84:85], v[84:85], s[6:7] op_sel_hi:[1,0]
	v_fma_f32 v103, -v143, |v85|, v89
	v_fma_f32 v102, -v142, |v84|, v88
	v_pk_add_f32 v[84:85], v[160:161], s[34:35] op_sel_hi:[0,1]
	v_fma_f32 v105, -v143, |v85|, v107
	v_fma_f32 v104, -v142, |v84|, v106
	v_pk_add_f32 v[86:87], v[160:161], s[36:37] op_sel_hi:[0,1]
	v_pk_add_f32 v[84:85], v[84:85], s[6:7] op_sel_hi:[1,0]
	v_fma_f32 v107, -v143, |v87|, v109
	v_fma_f32 v106, -v142, |v86|, v108
	v_fma_f32 v85, -v143, |v85|, v91
	v_fma_f32 v84, -v142, |v84|, v90
	v_pk_add_f32 v[86:87], v[86:87], s[6:7] op_sel_hi:[1,0]
	v_pk_add_f32 v[88:89], v[160:161], s[38:39] op_sel_hi:[0,1]
	v_fma_f32 v87, -v143, |v87|, v93
	v_fma_f32 v86, -v142, |v86|, v92
	v_fma_f32 v93, -v143, |v89|, v111
	v_fma_f32 v92, -v142, |v88|, v110
	v_pk_add_f32 v[88:89], v[88:89], s[6:7] op_sel_hi:[1,0]
	v_fma_f32 v89, -v143, |v89|, v95
	v_fma_f32 v88, -v142, |v88|, v94
	v_pk_add_f32 v[90:91], v[160:161], s[40:41] op_sel_hi:[0,1]
	v_fma_f32 v95, -v143, |v91|, v113
	v_fma_f32 v94, -v142, |v90|, v112
	v_pk_add_f32 v[90:91], v[90:91], s[6:7] op_sel_hi:[1,0]
	v_fma_f32 v91, -v143, |v91|, v97
	v_fma_f32 v90, -v142, |v90|, v96
; __device__ __forceinline__ float max3f(float a, float b, float c) { float r; asm("v_max3_f32 %0, %1, %2, %3" : "=v"(r) : "v"(a), "v"(b), "v"(c)); return r; }
; template <int DQK, int DV, bool BIAS> ...
;     ...
;         float mxa = max3f(p0[0], p0[1], p1[0]), mxb = max3f(p0[2], p0[3], p1[1]); mxa = max3f(mxa, p1[2], p1[3]);
; #pragma unroll
;         for (int r = 4; r < 16; r += 4) { mxa = max3f(mxa, p0[r], p0[r + 1]); mxb = max3f(mxb, p0[r + 2], p0[r + 3]); mxa = max3f(mxa, p1[r], p1[r + 1]); mxb = max3f(mxb, p1[r + 2], p1[r + 3]); }
;         float mx = fmaxf(mxa, mxb);
;         if (__any(mx > 8.f)) {
;             mx = fmaxf(mx, __shfl_xor(mx, 32));
;             const float dl = fmaxf(mx, 0.f); mhat += dl;
;             const float f = __builtin_amdgcn_exp2f(-dl);
; #pragma unroll
;             for (int r = 0; r < 16; ++r) { p0[r] -= dl; p1[r] -= dl; negm[r] = -mhat; }
;             l *= f;
; #pragma unroll
;             for (int d = 0; d < NDT; ++d)
; #pragma unroll
;                 for (int r = 0; r < 16; ++r) o[d][r] *= f;
;         }
.Lcb4_j:
	v_max3_f32 v96, v150, v151, v82
	v_max3_f32 v97, v152, v153, v83
	v_max3_f32 v96, v96, v98, v99
	v_max3_f32 v97, v97, v156, v157
	v_max3_f32 v96, v96, v154, v155
	v_max3_f32 v97, v97, v102, v103
	v_max3_f32 v96, v96, v100, v101
	v_max3_f32 v97, v97, v106, v107
	v_max3_f32 v96, v96, v104, v105
	v_max3_f32 v97, v97, v86, v87
	v_max3_f32 v96, v96, v84, v85
	v_max3_f32 v97, v97, v94, v95
	v_max3_f32 v96, v96, v92, v93
	v_max3_f32 v97, v97, v90, v91
	v_max3_f32 v96, v96, v88, v89
	v_max_f32_e32 v96, v96, v97
	v_cmp_gt_f32_e32 vcc, 0xc3400000, v96
	s_cmp_eq_u64 vcc, exec
	s_cbranch_scc1 .Lsk2_p4a2
	v_cmp_lt_f32_e32 vcc, s44, v96
	s_cbranch_vccz .LBB0_587
	ds_bpermute_b32 v66, v168, v96
	s_waitcnt lgkmcnt(0)
	v_max3_f32 v67, v96, v66, 0
	v_exp_f32_e64 v68, -v67
	v_add_f32_e32 v180, v180, v67
	v_xor_b32_e32 v66, 0x80000000, v180
	v_sub_f32_e32 v82, v82, v67
	v_sub_f32_e32 v83, v83, v67
	v_sub_f32_e32 v98, v98, v67
	v_sub_f32_e32 v99, v99, v67
	v_sub_f32_e32 v100, v100, v67
	v_sub_f32_e32 v101, v101, v67
	v_sub_f32_e32 v102, v102, v67
	v_sub_f32_e32 v103, v103, v67
	v_sub_f32_e32 v84, v84, v67
	v_sub_f32_e32 v85, v85, v67
	v_sub_f32_e32 v86, v86, v67
	v_sub_f32_e32 v87, v87, v67
	v_sub_f32_e32 v88, v88, v67
	v_sub_f32_e32 v89, v89, v67
	v_sub_f32_e32 v90, v90, v67
	v_sub_f32_e32 v91, v91, v67
	v_pk_mul_f32 v[16:17], v[16:17], v[68:69] op_sel_hi:[1,0]
	v_pk_mul_f32 v[14:15], v[14:15], v[68:69] op_sel_hi:[1,0]
	v_pk_mul_f32 v[12:13], v[12:13], v[68:69] op_sel_hi:[1,0]
	v_pk_mul_f32 v[10:11], v[10:11], v[68:69] op_sel_hi:[1,0]
	v_pk_mul_f32 v[8:9], v[8:9], v[68:69] op_sel_hi:[1,0]
	v_pk_mul_f32 v[6:7], v[6:7], v[68:69] op_sel_hi:[1,0]
	v_pk_mul_f32 v[4:5], v[4:5], v[68:69] op_sel_hi:[1,0]
	v_pk_mul_f32 v[2:3], v[2:3], v[68:69] op_sel_hi:[1,0]
	v_pk_mul_f32 v[32:33], v[32:33], v[68:69] op_sel_hi:[1,0]
	v_pk_mul_f32 v[30:31], v[30:31], v[68:69] op_sel_hi:[1,0]
	v_pk_mul_f32 v[28:29], v[28:29], v[68:69] op_sel_hi:[1,0]
	v_pk_mul_f32 v[26:27], v[26:27], v[68:69] op_sel_hi:[1,0]
	v_pk_mul_f32 v[24:25], v[24:25], v[68:69] op_sel_hi:[1,0]
	v_pk_mul_f32 v[22:23], v[22:23], v[68:69] op_sel_hi:[1,0]
	v_pk_mul_f32 v[20:21], v[20:21], v[68:69] op_sel_hi:[1,0]
	v_pk_mul_f32 v[18:19], v[18:19], v[68:69] op_sel_hi:[1,0]
	v_pk_mul_f32 v[48:49], v[48:49], v[68:69] op_sel_hi:[1,0]
	v_pk_mul_f32 v[46:47], v[46:47], v[68:69] op_sel_hi:[1,0]
	v_pk_mul_f32 v[44:45], v[44:45], v[68:69] op_sel_hi:[1,0]
	v_pk_mul_f32 v[42:43], v[42:43], v[68:69] op_sel_hi:[1,0]
	v_pk_mul_f32 v[40:41], v[40:41], v[68:69] op_sel_hi:[1,0]
	v_pk_mul_f32 v[38:39], v[38:39], v[68:69] op_sel_hi:[1,0]
	v_pk_mul_f32 v[36:37], v[36:37], v[68:69] op_sel_hi:[1,0]
	v_pk_mul_f32 v[34:35], v[34:35], v[68:69] op_sel_hi:[1,0]
	v_pk_mul_f32 v[64:65], v[64:65], v[68:69] op_sel_hi:[1,0]
	v_pk_mul_f32 v[62:63], v[62:63], v[68:69] op_sel_hi:[1,0]
	v_pk_mul_f32 v[60:61], v[60:61], v[68:69] op_sel_hi:[1,0]
	v_pk_mul_f32 v[58:59], v[58:59], v[68:69] op_sel_hi:[1,0]
	v_pk_mul_f32 v[56:57], v[56:57], v[68:69] op_sel_hi:[1,0]
	v_pk_mul_f32 v[54:55], v[54:55], v[68:69] op_sel_hi:[1,0]
	v_pk_mul_f32 v[52:53], v[52:53], v[68:69] op_sel_hi:[1,0]
	v_pk_mul_f32 v[50:51], v[50:51], v[68:69] op_sel_hi:[1,0]
	v_sub_f32_e32 v150, v150, v67
	v_sub_f32_e32 v151, v151, v67
	v_sub_f32_e32 v152, v152, v67
	v_sub_f32_e32 v153, v153, v67
	v_sub_f32_e32 v154, v154, v67
	v_sub_f32_e32 v155, v155, v67
	v_sub_f32_e32 v156, v156, v67
	v_sub_f32_e32 v157, v157, v67
	v_sub_f32_e32 v104, v104, v67
	v_sub_f32_e32 v105, v105, v67
	v_sub_f32_e32 v106, v106, v67
	v_sub_f32_e32 v107, v107, v67
	v_sub_f32_e32 v92, v92, v67
	v_sub_f32_e32 v93, v93, v67
	v_sub_f32_e32 v94, v94, v67
	v_sub_f32_e32 v95, v95, v67
	v_mul_f32_e32 v158, v158, v68
	v_mov_b32_e32 v250, v66
	v_fmamk_f32 v66, v251, 0x00000000, v250
	v_fmamk_f32 v67, v251, 0x3f800000, v250
	v_fmamk_f32 v68, v251, 0x40000000, v250
	v_fmamk_f32 v69, v251, 0x40400000, v250
	v_fmamk_f32 v70, v251, 0x41000000, v250
	v_fmamk_f32 v71, v251, 0x41100000, v250
	v_fmamk_f32 v72, v251, 0x41200000, v250
	v_fmamk_f32 v73, v251, 0x41300000, v250
	v_fmamk_f32 v74, v251, 0x41800000, v250
	v_fmamk_f32 v75, v251, 0x41880000, v250
	v_fmamk_f32 v76, v251, 0x41900000, v250
	v_fmamk_f32 v77, v251, 0x41980000, v250
	v_fmamk_f32 v78, v251, 0x41c00000, v250
	v_fmamk_f32 v79, v251, 0x41c80000, v250
	v_fmamk_f32 v80, v251, 0x41d00000, v250
	v_fmamk_f32 v81, v251, 0x41d80000, v250
	v_fmamk_f32 v234, v251, 0x42000000, v250
	v_fmamk_f32 v235, v251, 0x42040000, v250
	v_fmamk_f32 v236, v251, 0x42080000, v250
	v_fmamk_f32 v237, v251, 0x420c0000, v250
	v_fmamk_f32 v238, v251, 0x42200000, v250
	v_fmamk_f32 v239, v251, 0x42240000, v250
	v_fmamk_f32 v240, v251, 0x42280000, v250
	v_fmamk_f32 v241, v251, 0x422c0000, v250
	v_fmamk_f32 v242, v251, 0x42400000, v250
	v_fmamk_f32 v243, v251, 0x42440000, v250
	v_fmamk_f32 v244, v251, 0x42480000, v250
	v_fmamk_f32 v245, v251, 0x424c0000, v250
	v_fmamk_f32 v246, v251, 0x42600000, v250
	v_fmamk_f32 v247, v251, 0x42640000, v250
	v_fmamk_f32 v248, v251, 0x42680000, v250
	v_fmamk_f32 v249, v251, 0x426c0000, v250
	s_branch .LBB0_587

; template <int DQK, int DV, bool BIAS> ...
;     ...
;     for (int ks = 0; ks < NKS; ++ks) qf[ks] = ks < 4 ? *(const bf16x8*)(Qw + (size_t)r32 * ldq + ks * 16 + hi * 8) : *(const bf16x8*)(Q2w + (size_t)r32 * ldq2 + (ks - 4) * 16 + hi * 8);
; #pragma unroll
;     for (int ks = 0; ks < 4; ++ks) qf[ks] = scale_frag(qf[ks], cs);
;     if constexpr (DQK == 96) {
;         const float* rp = ropetab + ((size_t)(qpos0 + r32) * 16) * 2;
; #pragma unroll
;         for (int ks = 4; ks < 6; ++ks) {
;             const f32x4 c0 = *(const f32x4*)(rp + ((ks - 4) * 8 + hi * 4) * 2), c1 = *(const f32x4*)(rp + ((ks - 4) * 8 + hi * 4 + 2) * 2);
;             const u32x4 w = __builtin_bit_cast(u32x4, qf[ks]); u32x4 ow;
;             { const float a = bflo(w.x) * cs, b = bfhi(w.x) * cs; ow.x = cvtpk(a * c0[0] - b * c0[1], a * c0[1] + b * c0[0]); }
;             { const float a = bflo(w.y) * cs, b = bfhi(w.y) * cs; ow.y = cvtpk(a * c0[2] - b * c0[3], a * c0[3] + b * c0[2]); }
;             { const float a = bflo(w.z) * cs, b = bfhi(w.z) * cs; ow.z = cvtpk(a * c1[0] - b * c1[1], a * c1[1] + b * c1[0]); }
;             { const float a = bflo(w.w) * cs, b = bfhi(w.w) * cs; ow.w = cvtpk(a * c1[2] - b * c1[3], a * c1[3] + b * c1[2]); }
;             qf[ks] = __builtin_bit_cast(bf16x8, ow);
;         }
;     }
; #pragma unroll
;     for (int d = 0; d < NDT; ++d)
; #pragma unroll
;         for (int r = 0; r < 16; ++r) o[d][r] = 0.f;
; #pragma unroll
;     for (int ks = 0; ks < NKS; ++ks) asm volatile("" : "+v"(qf[ks]));
;     float mhat = 0.f, l = 0.f; f32x16 negm;
; __device__ __forceinline__ void attn_phase(PPtr P, int li, LAS unsigned char* lds, int vcu, int wave, int lane) {
;     bf16_t* proj = (bf16_t*)(P->ws + OFF_PROJ); bf16_t* mlaq = (bf16_t*)(P->ws + OFF_MLAQ); const bf16_t* mlakv = (const bf16_t*)(P->ws + OFF_MLAKV);
;     const int r32 = lane & 31, hi = lane >> 5;
;     {
;         const int b = vcu >> 6, h = (vcu >> 4) & 3, qb = vcu & 15;
;         const size_t seq0 = (size_t)b * SEQL, qrow = seq0 + qb * 256 + wave * 32;
;         const float slope = __builtin_amdgcn_exp2f(-2.f * (float)(h + 1));
;         f32x16 o1[4], o2[4];
;         attn_pass<64, 128, true>(lds, proj + qrow * LDP + C_AQ + h * 128, LDP, nullptr, 0, proj + seq0 * LDP + C_AK + h * 128, LDP, nullptr, 0, proj + seq0 * LDP + C_AV + h * 128, LDP, qb * 256 + wave * 32, 0.125f * LOG2E, slope * LOG2E, nullptr, o1);
.LBB0_2001:
	s_cmp_lt_i32 s24, 15
	s_cselect_b64 s[4:5], -1, 0
	s_cmp_gt_i32 s25, 14
	s_cselect_b64 s[6:7], -1, 0
	s_and_b64 s[4:5], s[4:5], s[6:7]
	s_andn2_b64 vcc, exec, s[4:5]
	s_cbranch_vccnz .LBB0_2179
	s_mov_b64 s[20:21], s[0:1]
	v_mov_b32_e32 v169, v1
	s_load_dwordx2 s[16:17], s[20:21], 0x118
	s_ashr_i32 s4, s33, 6
	v_readfirstlane_b32 s3, v169
	s_ashr_i32 s50, s3, 6
	s_ashr_i32 s5, s4, 31
	s_lshl_b32 s3, s33, 8
	s_lshl_b64 s[6:7], s[4:5], 12
	s_and_b32 s27, s3, 0xf00
	s_lshl_b32 s46, s50, 5
	s_bfe_u32 s8, s33, 0x20004
	s_or_b32 s3, s6, s27
	s_ashr_i32 s47, s46, 31
	s_add_u32 s5, s3, s46
	s_addc_u32 s6, s7, s47
	s_not_b32 s3, s8
	s_mulk_i32 s6, 0x1940
	s_mul_hi_u32 s7, s5, 0x1940
	s_lshl_b32 s3, s3, 1
	s_add_i32 s7, s7, s6
	s_mulk_i32 s5, 0x1940
	s_waitcnt lgkmcnt(0)
	s_add_u32 s5, s16, s5
	v_mov_b32_e32 v32, v1
	s_addc_u32 s6, s17, s7
	s_lshl_b32 s9, s8, 8
	s_add_u32 s18, s5, s9
	v_and_b32_e32 v33, 31, v32
	v_mul_u32_u24_e32 v2, 0xca0, v33
	s_addc_u32 s19, s6, 0
	v_bfe_u32 v34, v32, 5, 1
	v_lshlrev_b32_e32 v150, 1, v2
	v_mov_b32_e32 v151, 0
	v_lshl_add_u64 v[2:3], s[18:19], 0, v[150:151]
	v_lshlrev_b32_e32 v150, 4, v34
	v_lshl_add_u64 v[18:19], v[2:3], 0, v[150:151]
	global_load_dwordx4 v[2:5], v[18:19], off
	global_load_dwordx4 v[6:9], v[18:19], off offset:32
	global_load_dwordx4 v[10:13], v[18:19], off offset:64
	global_load_dwordx4 v[14:17], v[18:19], off offset:96
	s_movk_i32 s7, 0x1940
	s_mov_b32 s6, 0x3e38aa3b
	s_mul_i32 s49, s4, 0x1940000
	s_mul_hi_i32 s48, s4, 0x1940000
	s_add_u32 s4, s16, s49
	s_addc_u32 s5, s17, s48
	s_add_u32 s4, s4, s9
	s_addc_u32 s5, s5, 0
	s_mov_b32 s8, 0x65000
	v_lshlrev_b32_e32 v173, 2, v34
	s_mov_b32 s22, 0xc1000000
	s_mov_b32 s34, 0xc1200000
	s_mov_b32 s36, 0xc1800000
	s_mov_b32 s38, 0xc1900000
	s_mov_b32 s40, 0xc1c00000
	s_mov_b32 s42, 0xc1d00000
	s_mov_b32 s51, 0
	s_mov_b32 s23, 0xc1100000
	s_mov_b32 s35, 0xc1300000
	s_mov_b32 s37, 0xc1880000
	s_mov_b32 s39, 0xc1980000
	s_mov_b32 s41, 0xc1c80000
	s_mov_b32 s43, 0xc1d80000
	s_mov_b32 s52, 0x41000000
	v_mov_b32_e32 v176, v151
	v_mov_b32_e32 v66, v151
	v_mov_b32_e32 v67, v151
	v_mov_b32_e32 v68, v151
	v_mov_b32_e32 v69, v151
	v_mov_b32_e32 v70, v151
	v_mov_b32_e32 v71, v151
	v_mov_b32_e32 v72, v151
	v_mov_b32_e32 v73, v151
	v_mov_b32_e32 v74, v151
	v_mov_b32_e32 v75, v151
	v_mov_b32_e32 v76, v151
	v_mov_b32_e32 v77, v151
	v_mov_b32_e32 v78, v151
	v_mov_b32_e32 v79, v151
	v_mov_b32_e32 v80, v151
	v_mov_b32_e32 v81, v151
	s_waitcnt vmcnt(0)
; __device__ __forceinline__ unsigned cvtpk(float lo, float hi) { typedef __bf16 bf2 __attribute__((ext_vector_type(2))); f32x2 v = {lo, hi}; bf2 b = __builtin_convertvector(v, bf2); return __builtin_bit_cast(unsigned, b); }
; template <int DQK, int DV, bool BIAS> ...
;     ...
;     for (int ks = 0; ks < NKS; ++ks) qf[ks] = ks < 4 ? *(const bf16x8*)(Qw + (size_t)r32 * ldq + ks * 16 + hi * 8) : *(const bf16x8*)(Q2w + (size_t)r32 * ldq2 + (ks - 4) * 16 + hi * 8);
; #pragma unroll
;     for (int ks = 0; ks < 4; ++ks) qf[ks] = scale_frag(qf[ks], cs);
;     if constexpr (DQK == 96) {
;         const float* rp = ropetab + ((size_t)(qpos0 + r32) * 16) * 2;
; #pragma unroll
;         for (int ks = 4; ks < 6; ++ks) {
;             const f32x4 c0 = *(const f32x4*)(rp + ((ks - 4) * 8 + hi * 4) * 2), c1 = *(const f32x4*)(rp + ((ks - 4) * 8 + hi * 4 + 2) * 2);
;             const u32x4 w = __builtin_bit_cast(u32x4, qf[ks]); u32x4 ow;
;             { const float a = bflo(w.x) * cs, b = bfhi(w.x) * cs; ow.x = cvtpk(a * c0[0] - b * c0[1], a * c0[1] + b * c0[0]); }
;             { const float a = bflo(w.y) * cs, b = bfhi(w.y) * cs; ow.y = cvtpk(a * c0[2] - b * c0[3], a * c0[3] + b * c0[2]); }
;             { const float a = bflo(w.z) * cs, b = bfhi(w.z) * cs; ow.z = cvtpk(a * c1[0] - b * c1[1], a * c1[1] + b * c1[0]); }
;             { const float a = bflo(w.w) * cs, b = bfhi(w.w) * cs; ow.w = cvtpk(a * c1[2] - b * c1[3], a * c1[3] + b * c1[2]); }
;             qf[ks] = __builtin_bit_cast(bf16x8, ow);
;         }
;     }
; #pragma unroll
;     for (int d = 0; d < NDT; ++d)
; #pragma unroll
;         for (int r = 0; r < 16; ++r) o[d][r] = 0.f;
; #pragma unroll
;     for (int ks = 0; ks < NKS; ++ks) asm volatile("" : "+v"(qf[ks]));
;     float mhat = 0.f, l = 0.f; f32x16 negm;
; #pragma unroll
;     for (int r = 0; r < 16; ++r) negm[r] = 0.f;
;     constexpr int TPB = (DV == 64) ? 2 : 1, NG = SEQL / 64 / TPB;
;     u32x4 kreg[TPB], k2reg[TPB], vreg[TPB][NVL];
;     const bf16_t* kptr = Kg + (size_t)(tid >> 3) * ldk + (tid & 7) * 8;
;     const bf16_t* k2ptr = (DQK == 96) ? K2g + (size_t)(tid >> 2) * ldk2 + (tid & 3) * 8 : nullptr;
;     ...
;     u32x4 pw[4];
; #pragma unroll
;     for (int j = 0; j < TPB; ++j) { ATT_LOAD(j, j); ATT_STORE(j, j); }
; #pragma unroll
;     for (int j = 0; j < TPB; ++j) ATT_LOAD(TPB + j, j);
;     const float qp = (float)(qpos0 + r32);
	v_lshlrev_b32_e32 v18, 16, v2
	v_and_b32_e32 v19, 0xffff0000, v2
	v_lshlrev_b32_e32 v2, 16, v3
	v_and_b32_e32 v3, 0xffff0000, v3
	v_lshlrev_b32_e32 v30, 16, v14
	v_pk_mul_f32 v[2:3], v[2:3], s[6:7] op_sel_hi:[1,0]
	v_and_b32_e32 v31, 0xffff0000, v14
	v_cvt_pk_bf16_f32 v115, v2, v3
	v_pk_mul_f32 v[2:3], v[30:31], s[6:7] op_sel_hi:[1,0]
	v_lshlrev_b32_e32 v22, 16, v6
	v_cvt_pk_bf16_f32 v126, v2, v3
	v_lshlrev_b32_e32 v2, 16, v15
	v_and_b32_e32 v3, 0xffff0000, v15
	v_pk_mul_f32 v[2:3], v[2:3], s[6:7] op_sel_hi:[1,0]
	v_and_b32_e32 v23, 0xffff0000, v6
	v_cvt_pk_bf16_f32 v127, v2, v3
	v_lshlrev_b32_e32 v2, 16, v16
	v_and_b32_e32 v3, 0xffff0000, v16
	v_pk_mul_f32 v[2:3], v[2:3], s[6:7] op_sel_hi:[1,0]
	v_lshlrev_b32_e32 v24, 16, v8
	v_cvt_pk_bf16_f32 v128, v2, v3
	v_lshlrev_b32_e32 v2, 16, v17
	v_and_b32_e32 v3, 0xffff0000, v17
	v_and_b32_e32 v25, 0xffff0000, v8
	v_pk_mul_f32 v[22:23], v[22:23], s[6:7] op_sel_hi:[1,0]
	v_pk_mul_f32 v[2:3], v[2:3], s[6:7] op_sel_hi:[1,0]
	v_lshlrev_b32_e32 v20, 16, v4
	v_and_b32_e32 v21, 0xffff0000, v4
	v_lshlrev_b32_e32 v4, 16, v5
	v_and_b32_e32 v5, 0xffff0000, v5
	v_pk_mul_f32 v[24:25], v[24:25], s[6:7] op_sel_hi:[1,0]
	v_cvt_pk_bf16_f32 v118, v22, v23
	v_cvt_pk_bf16_f32 v129, v2, v3
	v_ashrrev_i32_e32 v22, 3, v32
	v_mov_b64_e32 v[2:3], s[4:5]
	v_lshlrev_b32_e32 v23, 4, v32
	v_pk_mul_f32 v[4:5], v[4:5], s[6:7] op_sel_hi:[1,0]
	v_cvt_pk_bf16_f32 v120, v24, v25
	v_mad_i64_i32 v[2:3], s[10:11], v22, s7, v[2:3]
	v_and_b32_e32 v14, 0x70, v23
	v_mov_b32_e32 v15, v151
	v_bfe_u32 v24, v32, 2, 6
	v_cvt_pk_bf16_f32 v117, v4, v5
	v_lshl_add_u64 v[144:145], v[2:3], 0, v[14:15]
	v_subrev_u32_e32 v232, s4, v144
	s_sub_u32 s98, s4, s16
	s_subb_u32 s99, s5, s17
	v_mul_u32_u24_e32 v2, 0xca0, v24
	v_lshlrev_b32_e32 v4, 3, v32
	v_lshlrev_b32_e32 v2, 1, v2
	v_mov_b32_e32 v3, v151
	v_and_b32_e32 v25, 24, v4
	v_lshl_add_u64 v[2:3], s[4:5], 0, v[2:3]
	v_lshlrev_b32_e32 v4, 1, v25
	v_mov_b32_e32 v5, v151
	v_lshl_add_u64 v[16:17], v[2:3], 0, v[4:5]
	v_and_b32_e32 v2, 0xffffffe0, v22
	v_lshlrev_b32_e32 v6, 16, v7
	v_and_b32_e32 v7, 0xffff0000, v7
	v_lshlrev_b32_e32 v8, 16, v9
	v_and_b32_e32 v9, 0xffff0000, v9
	v_lshlrev_b32_e32 v26, 16, v10
	v_and_b32_e32 v27, 0xffff0000, v10
	v_lshlrev_b32_e32 v10, 16, v11
	v_and_b32_e32 v11, 0xffff0000, v11
	v_lshlrev_b32_e32 v28, 16, v12
	v_and_b32_e32 v29, 0xffff0000, v12
	v_lshlrev_b32_e32 v12, 16, v13
	v_and_b32_e32 v13, 0xffff0000, v13
	v_pk_mul_f32 v[18:19], v[18:19], s[6:7] op_sel_hi:[1,0]
	v_ashrrev_i32_e32 v3, 31, v2
	v_pk_mul_f32 v[20:21], v[20:21], s[6:7] op_sel_hi:[1,0]
	v_pk_mul_f32 v[6:7], v[6:7], s[6:7] op_sel_hi:[1,0]
	v_pk_mul_f32 v[8:9], v[8:9], s[6:7] op_sel_hi:[1,0]
	v_pk_mul_f32 v[26:27], v[26:27], s[6:7] op_sel_hi:[1,0]
	v_pk_mul_f32 v[10:11], v[10:11], s[6:7] op_sel_hi:[1,0]
	v_pk_mul_f32 v[28:29], v[28:29], s[6:7] op_sel_hi:[1,0]
	v_pk_mul_f32 v[12:13], v[12:13], s[6:7] op_sel_hi:[1,0]
	v_cvt_pk_bf16_f32 v114, v18, v19
	v_lshlrev_b64 v[18:19], 1, v[2:3]
	v_cvt_pk_bf16_f32 v116, v20, v21
	v_cvt_pk_bf16_f32 v119, v6, v7
	v_cvt_pk_bf16_f32 v121, v8, v9
	v_cvt_pk_bf16_f32 v122, v26, v27
	v_cvt_pk_bf16_f32 v123, v10, v11
	v_cvt_pk_bf16_f32 v124, v28, v29
	v_cvt_pk_bf16_f32 v125, v12, v13
	v_lshl_add_u64 v[10:11], v[16:17], 0, v[18:19]
	global_load_dwordx4 v[2:5], v[144:145], off offset:1024
	global_load_dwordx4 v[6:9], v[10:11], off offset:2048
	v_add_u32_e32 v10, 0x200, v32
	v_ashrrev_i32_e32 v10, 3, v10
	v_and_b32_e32 v10, 0xffffffe0, v10
	v_ashrrev_i32_e32 v11, 31, v10
	v_lshlrev_b64 v[20:21], 1, v[10:11]
	v_lshl_add_u64 v[10:11], v[16:17], 0, v[20:21]
	global_load_dwordx4 v[10:13], v[10:11], off offset:2048
	s_movk_i32 s6, 0x90
	v_mul_lo_u32 v15, v22, s6
	s_mov_b64 s[10:11], 0x65800
	v_and_b32_e32 v22, 0xfc0, v23
	v_and_b32_e32 v27, 48, v23
	v_add_u32_e32 v15, 0, v15
	v_and_b32_e32 v23, 0xfffff000, v23
	v_add3_u32 v22, 0, v22, v27
	v_add_u32_e32 v168, v15, v14
	v_lshl_add_u64 v[14:15], v[16:17], 0, s[10:11]
	v_add_u32_e32 v171, v22, v23
	v_lshl_add_u64 v[16:17], v[14:15], 0, v[18:19]
	v_add_co_u32_e32 v22, vcc, s8, v144
	v_lshl_add_u64 v[14:15], v[14:15], 0, v[20:21]
	s_nop 0
	v_addc_co_u32_e32 v23, vcc, 0, v145, vcc
	global_load_dwordx4 v[130:133], v[16:17], off
	global_load_dwordx4 v[134:137], v[14:15], off
	global_load_dwordx4 v[138:141], v[22:23], off offset:1024
	v_cvt_f32_i32_e32 v28, s3
	s_add_i32 s3, s46, s27
	v_lshrrev_b32_e32 v26, 2, v32
	s_waitcnt vmcnt(5)
	ds_write_b128 v168, v[2:5]
	s_waitcnt vmcnt(4)
	ds_write_b128 v171, v[6:9] offset:18432
	s_waitcnt vmcnt(3)
	ds_write_b128 v171, v[10:13] offset:26624
	v_or_b32_e32 v2, s3, v33
	v_cvt_f32_i32_e32 v172, v2
	v_and_or_b32 v2, v26, 3, v173
	v_lshlrev_b32_e32 v3, 1, v32
	v_mad_u32_u24 v22, v33, s6, 0
	v_lshl_add_u32 v2, v2, 6, 0
	v_and_b32_e32 v3, 32, v3
	s_or_b32 s6, s49, s9
	v_exp_f32_e32 v27, v28
	v_add3_u32 v174, v2, v3, v25
	v_mov_b32_e32 v2, s6
	v_mov_b32_e32 v3, s48
	v_mad_u64_u32 v[2:3], s[6:7], v24, s7, v[2:3]
	v_and_b32_e32 v4, 3, v32
	v_lshl_or_b32 v2, v4, 4, v2
	v_lshl_add_u64 v[4:5], v[2:3], 0, v[20:21]
	v_lshl_add_u64 v[2:3], v[2:3], 0, v[18:19]
	v_mov_b32_e32 v16, v151
	v_mov_b32_e32 v17, v151
	v_mbcnt_lo_u32_b32 v18, -1, 0
	v_mul_f32_e32 v142, 0x3fb8aa3b, v27
	v_mov_b32_e32 v231, v4
	v_lshl_add_u64 v[146:147], s[16:17], 0, v[4:5]
	v_mov_b32_e32 v230, v2
	v_lshl_add_u64 v[148:149], s[16:17], 0, v[2:3]
	v_mov_b32_e32 v2, v151
	v_mov_b32_e32 v3, v151
	v_mov_b32_e32 v4, v151
	v_mov_b32_e32 v5, v151
	v_mov_b32_e32 v6, v151
	v_mov_b32_e32 v7, v151
	v_mov_b32_e32 v8, v151
	v_mov_b32_e32 v9, v151
	v_mov_b32_e32 v10, v151
	v_mov_b32_e32 v11, v151
	v_mov_b32_e32 v12, v151
	v_mov_b32_e32 v13, v151
	v_mov_b32_e32 v14, v151
	v_mov_b32_e32 v15, v151
	s_mov_b32 s10, -2.0
	v_add_u32_e32 v175, v22, v150
	v_mbcnt_hi_u32_b32 v170, -1, v18
	v_mov_b64_e32 v[32:33], v[16:17]
	v_mov_b64_e32 v[48:49], v[16:17]
	v_mov_b64_e32 v[64:65], v[16:17]
	v_mov_b32_e32 v143, v142
	s_mov_b64 s[6:7], 0
	s_mov_b32 s8, 0xc2000000
	s_mov_b32 s11, 0xc0400000
	v_mov_b64_e32 v[30:31], v[14:15]
	v_mov_b64_e32 v[28:29], v[12:13]
	v_mov_b64_e32 v[26:27], v[10:11]
	v_mov_b64_e32 v[24:25], v[8:9]
	v_mov_b64_e32 v[22:23], v[6:7]
	v_mov_b64_e32 v[20:21], v[4:5]
	v_mov_b64_e32 v[18:19], v[2:3]
	v_mov_b64_e32 v[46:47], v[14:15]
	v_mov_b64_e32 v[44:45], v[12:13]
	v_mov_b64_e32 v[42:43], v[10:11]
	v_mov_b64_e32 v[40:41], v[8:9]
	v_mov_b64_e32 v[38:39], v[6:7]
	v_mov_b64_e32 v[36:37], v[4:5]
	v_mov_b64_e32 v[34:35], v[2:3]
	v_mov_b64_e32 v[62:63], v[14:15]
	v_mov_b64_e32 v[60:61], v[12:13]
	v_mov_b64_e32 v[58:59], v[10:11]
	v_mov_b64_e32 v[56:57], v[8:9]
	v_mov_b64_e32 v[54:55], v[6:7]
	v_mov_b64_e32 v[52:53], v[4:5]
	v_mov_b64_e32 v[50:51], v[2:3]
	v_mov_b32_e32 v250, 0
	v_cvt_u32_f32_e32 v252, v172
	s_nop 0
	v_readfirstlane_b32 s96, v252
	s_nop 3
	s_lshr_b32 s96, s96, 6
	s_mov_b32 s97, 3
	s_branch .LBB0_2004
